# best + K-loop back-edge SALU block (counter, K offset, exit test) moved in front of the loop's last barrier
# speedup vs baseline: 1.0029x; 1.0029x over previous
; #define PG8_STAGE(bufoff, gbase, voff) do { _Pragma("unroll") for (int _i = 0; _i < 2; ++_i) \
;         __builtin_amdgcn_global_load_lds((const unsigned*)((const char*)(gbase) + (voff)[_i]), (PG8_LAS unsigned*)(lds + (bufoff) + ldsw + _i * 8192), 16, 0, 0); } while (0)
; #define PG8_LDA(dst, b, h) do { _Pragma("unroll") for (int m = 0; m < 4; ++m) _Pragma("unroll") for (int k = 0; k < 2; ++k) dst[m][k] = *(const PG8_LAS bf16x8*)(lds + PG8_SA(b, h) + aoff + m * 2048 + k * 1024); } while (0)
; #define PG8_LDB(dst, b, h) do { _Pragma("unroll") for (int n = 0; n < 2; ++n) _Pragma("unroll") for (int k = 0; k < 2; ++k) dst[n][k] = *(const PG8_LAS bf16x8*)(lds + PG8_SB(b, h) + boff + n * 2048 + k * 1024); } while (0)
; #define PG8_MMA(ai, bj, At, Bt) do { __builtin_amdgcn_s_setprio(1); _Pragma("unroll") for (int m = 0; m < 4; ++m) _Pragma("unroll") for (int n = 0; n < 2; ++n) _Pragma("unroll") for (int k = 0; k < 2; ++k) \
;         acc[ai][bj][m][n] = __builtin_amdgcn_mfma_f32_16x16x32_bf16(Bt[n][k], At[m][k], acc[ai][bj][m][n], 0, 0, 0); __builtin_amdgcn_s_setprio(0); } while (0)
; #define PG8_WAIT_V(n) asm volatile("s_waitcnt vmcnt(" #n ")" ::: "memory")
; #define PG8_BAR __builtin_amdgcn_s_barrier()
; template <class Epi, class Sched, bool ALIGN_EPI = false, bool SP2 = false>
; __device__ __forceinline__ void gemm_phase(PG8_LAS unsigned char* lds, const Gemm g, const Sched& S, const Epi& E) {
;     ...
;         for (int t = 0; t < nt; t += 2) {
;             const bool last = (t == nt - 2);
;             const char* a1 = cA + (size_t)(t + 1) * kstep;
;             const char* a2 = last ? nA : cA + (size_t)(t + 2) * kstep; const char* b2 = last ? nB : cB + (size_t)(t + 2) * kstep;
;             const char* a3 = a2 + kstep; const char* b3 = b2 + kstep;
;             if (last && has_next) S.a_ready(nxt);
;             if constexpr (SP2) {
;             PG8_LDB(B0, 0, 0); PG8_LDB(B1, 0, 1); PG8_SCHED; PG8_LDA(At, 0, 0); PG8_STAGE(PG8_SA(1, 1), a1 + hstepA, voffA);
;             PG8_WAIT_V(8); PG8_WAIT_L(0); PG8_BAR; PG8_MMA(0, 0, At, B0); PG8_MMA(0, 1, At, B1); PG8_BAR; PG8_SCHED;
;             PG8_LDA(At, 0, 1); PG8_STAGE(PG8_SB(0, 0), b2, voffB); PG8_STAGE(PG8_SB(0, 1), b2 + hstepB, voffB); PG8_STAGE(PG8_SA(0, 0), a2, voffA);
;             PG8_WAIT_V(8); PG8_WAIT_L(0); PG8_BAR; PG8_MMA(1, 0, At, B0); PG8_MMA(1, 1, At, B1); PG8_BAR; PG8_SCHED;
.LBB0_87:
	s_add_u32 s22, s10, s4
	s_addc_u32 s23, s11, s5
	s_add_u32 s22, s22, 0x4900100
	s_addc_u32 s23, s23, 0
	s_add_u32 s62, s54, s4
	s_addc_u32 s67, s55, s5
	s_add_i32 s69, 0, 0x10000
	s_cmpk_eq_i32 s4, 0x700
	s_cselect_b32 s25, s15, s23
	s_cselect_b32 s24, s14, s22
	v_add_u32_e32 v155, s69, v153
	s_cselect_b32 s23, s46, s67
	s_cselect_b32 s22, s53, s62
	s_add_i32 s62, 0, 0x14000
	ds_read_b128 v[130:133], v155
	ds_read_b128 v[148:151], v155 offset:1024
	ds_read_b128 v[156:159], v155 offset:2048
	ds_read_b128 v[160:163], v155 offset:3072
	v_add_u32_e32 v155, s62, v153
	ds_read_b128 v[164:167], v155
	ds_read_b128 v[168:171], v155 offset:1024
	ds_read_b128 v[172:175], v155 offset:2048
	ds_read_b128 v[176:179], v155 offset:3072
	v_lshl_add_u64 v[204:205], v[144:145], 0, s[4:5]
	s_add_i32 m0, s13, 0xc000
	ds_read_b128 v[180:183], v154
	ds_read_b128 v[184:187], v154 offset:1024
	ds_read_b128 v[188:191], v154 offset:2048
	ds_read_b128 v[192:195], v154 offset:3072
	ds_read_b128 v[196:199], v154 offset:4096
	ds_read_b128 v[200:203], v154 offset:5120
	ds_read_b128 v[208:211], v154 offset:6144
	ds_read_b128 v[212:215], v154 offset:7168
	global_load_lds_dwordx4 v[204:205], off
	v_lshl_add_u64 v[204:205], v[146:147], 0, s[4:5]
	s_add_i32 m0, s13, 0xe000
	s_nop 0
	global_load_lds_dwordx4 v[204:205], off
	s_waitcnt vmcnt(8)
	s_waitcnt lgkmcnt(0)
	s_barrier
	s_setprio 1
	s_waitcnt lgkmcnt(0)
	v_mfma_f32_16x16x32_bf16 v[126:129], v[130:133], v[180:183], v[126:129]
	v_mfma_f32_16x16x32_bf16 v[122:125], v[156:159], v[180:183], v[122:125]
	v_mfma_f32_16x16x32_bf16 v[118:121], v[130:133], v[188:191], v[118:121]
	v_mfma_f32_16x16x32_bf16 v[114:117], v[156:159], v[188:191], v[114:117]
	v_mfma_f32_16x16x32_bf16 v[110:113], v[130:133], v[196:199], v[110:113]
	v_mfma_f32_16x16x32_bf16 v[106:109], v[156:159], v[196:199], v[106:109]
	v_mfma_f32_16x16x32_bf16 v[102:105], v[130:133], v[208:211], v[102:105]
	v_mfma_f32_16x16x32_bf16 v[98:101], v[156:159], v[208:211], v[98:101]
	v_mfma_f32_16x16x32_bf16 v[126:129], v[148:151], v[184:187], v[126:129]
	v_mfma_f32_16x16x32_bf16 v[122:125], v[160:163], v[184:187], v[122:125]
	v_mfma_f32_16x16x32_bf16 v[118:121], v[148:151], v[192:195], v[118:121]
	v_mfma_f32_16x16x32_bf16 v[114:117], v[160:163], v[192:195], v[114:117]
	v_mfma_f32_16x16x32_bf16 v[110:113], v[148:151], v[200:203], v[110:113]
	v_mfma_f32_16x16x32_bf16 v[106:109], v[160:163], v[200:203], v[106:109]
	v_mfma_f32_16x16x32_bf16 v[102:105], v[148:151], v[212:215], v[102:105]
	v_mfma_f32_16x16x32_bf16 v[98:101], v[160:163], v[212:215], v[98:101]
	s_setprio 0
	s_setprio 1
	v_mfma_f32_16x16x32_bf16 v[60:63], v[164:167], v[180:183], v[60:63]
	v_mfma_f32_16x16x32_bf16 v[56:59], v[172:175], v[180:183], v[56:59]
	v_mfma_f32_16x16x32_bf16 v[52:55], v[164:167], v[188:191], v[52:55]
	v_mfma_f32_16x16x32_bf16 v[48:51], v[172:175], v[188:191], v[48:51]
	v_mfma_f32_16x16x32_bf16 v[44:47], v[164:167], v[196:199], v[44:47]
	v_mfma_f32_16x16x32_bf16 v[40:43], v[172:175], v[196:199], v[40:43]
	v_mfma_f32_16x16x32_bf16 v[36:39], v[164:167], v[208:211], v[36:39]
	v_mfma_f32_16x16x32_bf16 v[32:35], v[172:175], v[208:211], v[32:35]
	v_mfma_f32_16x16x32_bf16 v[60:63], v[168:171], v[184:187], v[60:63]
	v_mfma_f32_16x16x32_bf16 v[56:59], v[176:179], v[184:187], v[56:59]
	v_mfma_f32_16x16x32_bf16 v[52:55], v[168:171], v[192:195], v[52:55]
	v_mfma_f32_16x16x32_bf16 v[48:51], v[176:179], v[192:195], v[48:51]
	v_mfma_f32_16x16x32_bf16 v[44:47], v[168:171], v[200:203], v[44:47]
	v_mfma_f32_16x16x32_bf16 v[40:43], v[176:179], v[200:203], v[40:43]
	v_mfma_f32_16x16x32_bf16 v[36:39], v[168:171], v[212:215], v[36:39]
	v_mfma_f32_16x16x32_bf16 v[32:35], v[176:179], v[212:215], v[32:35]
	s_setprio 0
	s_barrier
	s_add_i32 s67, s69, s28
	v_lshl_add_u64 v[204:205], s[22:23], 0, v[138:139]
	s_mov_b32 m0, s67
	ds_read_b128 v[180:183], v154 offset:16384
	ds_read_b128 v[184:187], v154 offset:17408
	ds_read_b128 v[188:191], v154 offset:18432
	ds_read_b128 v[192:195], v154 offset:19456
	ds_read_b128 v[196:199], v154 offset:20480
	ds_read_b128 v[200:203], v154 offset:21504
	ds_read_b128 v[208:211], v154 offset:22528
	ds_read_b128 v[212:215], v154 offset:23552
	global_load_lds_dwordx4 v[204:205], off
	s_add_i32 m0, s67, 0x2000
	s_add_u32 s70, s22, 0x40000
	v_lshl_add_u64 v[216:217], s[22:23], 0, v[134:135]
	s_addc_u32 s71, s23, 0
	s_add_i32 s62, s62, s28
	global_load_lds_dwordx4 v[216:217], off
	v_lshl_add_u64 v[218:219], s[70:71], 0, v[138:139]
	s_mov_b32 m0, s62
	v_lshl_add_u64 v[222:223], s[24:25], 0, v[136:137]
	global_load_lds_dwordx4 v[218:219], off
	v_lshl_add_u64 v[218:219], s[70:71], 0, v[134:135]
	s_add_i32 m0, s62, 0x2000
	s_nop 0
	global_load_lds_dwordx4 v[218:219], off
	v_lshl_add_u64 v[218:219], s[24:25], 0, v[64:65]
	s_mov_b32 m0, s13
	s_nop 0
	global_load_lds_dwordx4 v[218:219], off
	s_mov_b32 m0, s30
	s_nop 0
	global_load_lds_dwordx4 v[222:223], off
	s_waitcnt vmcnt(8)
	s_waitcnt lgkmcnt(0)
	s_barrier
; #define PG8_STAGE(bufoff, gbase, voff) do { _Pragma("unroll") for (int _i = 0; _i < 2; ++_i) \
;         __builtin_amdgcn_global_load_lds((const unsigned*)((const char*)(gbase) + (voff)[_i]), (PG8_LAS unsigned*)(lds + (bufoff) + ldsw + _i * 8192), 16, 0, 0); } while (0)
; #define PG8_LDA(dst, b, h) do { _Pragma("unroll") for (int m = 0; m < 4; ++m) _Pragma("unroll") for (int k = 0; k < 2; ++k) dst[m][k] = *(const PG8_LAS bf16x8*)(lds + PG8_SA(b, h) + aoff + m * 2048 + k * 1024); } while (0)
; #define PG8_LDB(dst, b, h) do { _Pragma("unroll") for (int n = 0; n < 2; ++n) _Pragma("unroll") for (int k = 0; k < 2; ++k) dst[n][k] = *(const PG8_LAS bf16x8*)(lds + PG8_SB(b, h) + boff + n * 2048 + k * 1024); } while (0)
; #define PG8_MMA(ai, bj, At, Bt) do { __builtin_amdgcn_s_setprio(1); _Pragma("unroll") for (int m = 0; m < 4; ++m) _Pragma("unroll") for (int n = 0; n < 2; ++n) _Pragma("unroll") for (int k = 0; k < 2; ++k) \
;         acc[ai][bj][m][n] = __builtin_amdgcn_mfma_f32_16x16x32_bf16(Bt[n][k], At[m][k], acc[ai][bj][m][n], 0, 0, 0); __builtin_amdgcn_s_setprio(0); } while (0)
; #define PG8_WAIT_V(n) asm volatile("s_waitcnt vmcnt(" #n ")" ::: "memory")
; #define PG8_WAIT_L(n) asm volatile("s_waitcnt lgkmcnt(" #n ")" ::: "memory")
; #define PG8_BAR __builtin_amdgcn_s_barrier()
; #define PG8_SCHED __builtin_amdgcn_sched_barrier(0)
; template <class Epi, class Sched, bool ALIGN_EPI = false, bool SP2 = false>
; __device__ __forceinline__ void gemm_phase(PG8_LAS unsigned char* lds, const Gemm g, const Sched& S, const Epi& E) {
;     ...
;             PG8_WAIT_V(8); PG8_WAIT_L(0); PG8_BAR; PG8_MMA(1, 0, At, B0); PG8_MMA(1, 1, At, B1); PG8_BAR; PG8_SCHED;
;             PG8_LDB(B0, 1, 0); PG8_LDB(B1, 1, 1); PG8_SCHED; PG8_LDA(At, 1, 0); PG8_STAGE(PG8_SA(0, 1), a2 + hstepA, voffA);
;             PG8_WAIT_V(8); PG8_WAIT_L(0); PG8_BAR; PG8_MMA(0, 0, At, B0); PG8_MMA(0, 1, At, B1); PG8_BAR; PG8_SCHED;
	s_setprio 1
	s_waitcnt lgkmcnt(0)
	v_mfma_f32_16x16x32_bf16 v[94:97], v[130:133], v[180:183], v[94:97]
	v_mfma_f32_16x16x32_bf16 v[90:93], v[156:159], v[180:183], v[90:93]
	v_mfma_f32_16x16x32_bf16 v[86:89], v[130:133], v[188:191], v[86:89]
	v_mfma_f32_16x16x32_bf16 v[82:85], v[156:159], v[188:191], v[82:85]
	v_mfma_f32_16x16x32_bf16 v[78:81], v[130:133], v[196:199], v[78:81]
	v_mfma_f32_16x16x32_bf16 v[74:77], v[156:159], v[196:199], v[74:77]
	v_mfma_f32_16x16x32_bf16 v[70:73], v[130:133], v[208:211], v[70:73]
	v_mfma_f32_16x16x32_bf16 v[66:69], v[156:159], v[208:211], v[66:69]
	v_mfma_f32_16x16x32_bf16 v[94:97], v[148:151], v[184:187], v[94:97]
	v_mfma_f32_16x16x32_bf16 v[90:93], v[160:163], v[184:187], v[90:93]
	v_mfma_f32_16x16x32_bf16 v[86:89], v[148:151], v[192:195], v[86:89]
	v_mfma_f32_16x16x32_bf16 v[82:85], v[160:163], v[192:195], v[82:85]
	v_mfma_f32_16x16x32_bf16 v[78:81], v[148:151], v[200:203], v[78:81]
	v_mfma_f32_16x16x32_bf16 v[74:77], v[160:163], v[200:203], v[74:77]
	v_mfma_f32_16x16x32_bf16 v[70:73], v[148:151], v[212:215], v[70:73]
	v_mfma_f32_16x16x32_bf16 v[66:69], v[160:163], v[212:215], v[66:69]
	s_setprio 0
	s_setprio 1
	v_mfma_f32_16x16x32_bf16 v[28:31], v[164:167], v[180:183], v[28:31]
	v_mfma_f32_16x16x32_bf16 v[24:27], v[172:175], v[180:183], v[24:27]
	v_mfma_f32_16x16x32_bf16 v[20:23], v[164:167], v[188:191], v[20:23]
	v_mfma_f32_16x16x32_bf16 v[16:19], v[172:175], v[188:191], v[16:19]
	v_mfma_f32_16x16x32_bf16 v[12:15], v[164:167], v[196:199], v[12:15]
	v_mfma_f32_16x16x32_bf16 v[8:11], v[172:175], v[196:199], v[8:11]
	v_mfma_f32_16x16x32_bf16 v[4:7], v[164:167], v[208:211], v[4:7]
	v_mfma_f32_16x16x32_bf16 v[0:3], v[172:175], v[208:211], v[0:3]
	v_mfma_f32_16x16x32_bf16 v[28:31], v[168:171], v[184:187], v[28:31]
	v_mfma_f32_16x16x32_bf16 v[24:27], v[176:179], v[184:187], v[24:27]
	v_mfma_f32_16x16x32_bf16 v[20:23], v[168:171], v[192:195], v[20:23]
	v_mfma_f32_16x16x32_bf16 v[16:19], v[176:179], v[192:195], v[16:19]
	v_mfma_f32_16x16x32_bf16 v[12:15], v[168:171], v[200:203], v[12:15]
	v_mfma_f32_16x16x32_bf16 v[8:11], v[176:179], v[200:203], v[8:11]
	v_mfma_f32_16x16x32_bf16 v[4:7], v[168:171], v[212:215], v[4:7]
	v_mfma_f32_16x16x32_bf16 v[0:3], v[176:179], v[212:215], v[0:3]
	s_setprio 0
	s_barrier
	s_add_i32 s62, 0, 0x18000
	v_add_u32_e32 v155, s62, v153
	s_add_i32 s67, 0, 0x1c000
	ds_read_b128 v[130:133], v155
	ds_read_b128 v[148:151], v155 offset:1024
	ds_read_b128 v[156:159], v155 offset:2048
	ds_read_b128 v[160:163], v155 offset:3072
	v_add_u32_e32 v155, s67, v153
	ds_read_b128 v[164:167], v155
	ds_read_b128 v[168:171], v155 offset:1024
	ds_read_b128 v[172:175], v155 offset:2048
	ds_read_b128 v[176:179], v155 offset:3072
	s_add_u32 s24, s24, 0x40000
	s_addc_u32 s25, s25, 0
	s_mov_b32 m0, s31
	v_lshl_add_u64 v[224:225], s[24:25], 0, v[64:65]
	ds_read_b128 v[180:183], v154 offset:32768
	ds_read_b128 v[184:187], v154 offset:33792
	ds_read_b128 v[188:191], v154 offset:34816
	ds_read_b128 v[192:195], v154 offset:35840
	ds_read_b128 v[196:199], v154 offset:36864
	ds_read_b128 v[200:203], v154 offset:37888
	ds_read_b128 v[208:211], v154 offset:38912
	ds_read_b128 v[212:215], v154 offset:39936
	global_load_lds_dwordx4 v[224:225], off
	v_lshl_add_u64 v[224:225], s[24:25], 0, v[136:137]
	s_mov_b32 m0, s34
	s_nop 0
	global_load_lds_dwordx4 v[224:225], off
	s_waitcnt vmcnt(8)
	s_waitcnt lgkmcnt(0)
	s_barrier
	s_setprio 1
	s_waitcnt lgkmcnt(0)
	v_mfma_f32_16x16x32_bf16 v[126:129], v[130:133], v[180:183], v[126:129]
	v_mfma_f32_16x16x32_bf16 v[122:125], v[156:159], v[180:183], v[122:125]
	v_mfma_f32_16x16x32_bf16 v[118:121], v[130:133], v[188:191], v[118:121]
	v_mfma_f32_16x16x32_bf16 v[114:117], v[156:159], v[188:191], v[114:117]
	v_mfma_f32_16x16x32_bf16 v[110:113], v[130:133], v[196:199], v[110:113]
	v_mfma_f32_16x16x32_bf16 v[106:109], v[156:159], v[196:199], v[106:109]
	v_mfma_f32_16x16x32_bf16 v[102:105], v[130:133], v[208:211], v[102:105]
	v_mfma_f32_16x16x32_bf16 v[98:101], v[156:159], v[208:211], v[98:101]
	v_mfma_f32_16x16x32_bf16 v[126:129], v[148:151], v[184:187], v[126:129]
	v_mfma_f32_16x16x32_bf16 v[122:125], v[160:163], v[184:187], v[122:125]
	v_mfma_f32_16x16x32_bf16 v[118:121], v[148:151], v[192:195], v[118:121]
	v_mfma_f32_16x16x32_bf16 v[114:117], v[160:163], v[192:195], v[114:117]
	v_mfma_f32_16x16x32_bf16 v[110:113], v[148:151], v[200:203], v[110:113]
	v_mfma_f32_16x16x32_bf16 v[106:109], v[160:163], v[200:203], v[106:109]
	v_mfma_f32_16x16x32_bf16 v[102:105], v[148:151], v[212:215], v[102:105]
	v_mfma_f32_16x16x32_bf16 v[98:101], v[160:163], v[212:215], v[98:101]
	s_setprio 0
	s_setprio 1
	v_mfma_f32_16x16x32_bf16 v[60:63], v[164:167], v[180:183], v[60:63]
	v_mfma_f32_16x16x32_bf16 v[56:59], v[172:175], v[180:183], v[56:59]
	v_mfma_f32_16x16x32_bf16 v[52:55], v[164:167], v[188:191], v[52:55]
	v_mfma_f32_16x16x32_bf16 v[48:51], v[172:175], v[188:191], v[48:51]
	v_mfma_f32_16x16x32_bf16 v[44:47], v[164:167], v[196:199], v[44:47]
	v_mfma_f32_16x16x32_bf16 v[40:43], v[172:175], v[196:199], v[40:43]
	v_mfma_f32_16x16x32_bf16 v[36:39], v[164:167], v[208:211], v[36:39]
	v_mfma_f32_16x16x32_bf16 v[32:35], v[172:175], v[208:211], v[32:35]
	v_mfma_f32_16x16x32_bf16 v[60:63], v[168:171], v[184:187], v[60:63]
	v_mfma_f32_16x16x32_bf16 v[56:59], v[176:179], v[184:187], v[56:59]
	v_mfma_f32_16x16x32_bf16 v[52:55], v[168:171], v[192:195], v[52:55]
	v_mfma_f32_16x16x32_bf16 v[48:51], v[176:179], v[192:195], v[48:51]
	v_mfma_f32_16x16x32_bf16 v[44:47], v[168:171], v[200:203], v[44:47]
	v_mfma_f32_16x16x32_bf16 v[40:43], v[176:179], v[200:203], v[40:43]
	v_mfma_f32_16x16x32_bf16 v[36:39], v[168:171], v[212:215], v[36:39]
	v_mfma_f32_16x16x32_bf16 v[32:35], v[176:179], v[212:215], v[32:35]
	s_setprio 0
	s_barrier
; #define PG8_STAGE(bufoff, gbase, voff) do { _Pragma("unroll") for (int _i = 0; _i < 2; ++_i) \
;         __builtin_amdgcn_global_load_lds((const unsigned*)((const char*)(gbase) + (voff)[_i]), (PG8_LAS unsigned*)(lds + (bufoff) + ldsw + _i * 8192), 16, 0, 0); } while (0)
; #define PG8_LDA(dst, b, h) do { _Pragma("unroll") for (int m = 0; m < 4; ++m) _Pragma("unroll") for (int k = 0; k < 2; ++k) dst[m][k] = *(const PG8_LAS bf16x8*)(lds + PG8_SA(b, h) + aoff + m * 2048 + k * 1024); } while (0)
; #define PG8_MMA(ai, bj, At, Bt) do { __builtin_amdgcn_s_setprio(1); _Pragma("unroll") for (int m = 0; m < 4; ++m) _Pragma("unroll") for (int n = 0; n < 2; ++n) _Pragma("unroll") for (int k = 0; k < 2; ++k) \
;         acc[ai][bj][m][n] = __builtin_amdgcn_mfma_f32_16x16x32_bf16(Bt[n][k], At[m][k], acc[ai][bj][m][n], 0, 0, 0); __builtin_amdgcn_s_setprio(0); } while (0)
; #define PG8_WAIT_V(n) asm volatile("s_waitcnt vmcnt(" #n ")" ::: "memory")
; #define PG8_WAIT_L(n) asm volatile("s_waitcnt lgkmcnt(" #n ")" ::: "memory")
; #define PG8_BAR __builtin_amdgcn_s_barrier()
; #define PG8_SCHED __builtin_amdgcn_sched_barrier(0)
; template <class Epi, class Sched, bool ALIGN_EPI = false, bool SP2 = false>
; __device__ __forceinline__ void gemm_phase(PG8_LAS unsigned char* lds, const Gemm g, const Sched& S, const Epi& E) {
;     ...
;         for (int t = 0; t < nt; t += 2) {
;             const bool last = (t == nt - 2);
;     ...
;             PG8_LDA(At, 1, 1); PG8_STAGE(PG8_SB(1, 0), b3, voffB); PG8_STAGE(PG8_SB(1, 1), b3 + hstepB, voffB); PG8_STAGE(PG8_SA(1, 0), a3, voffA);
;             PG8_WAIT_V(8); PG8_WAIT_L(0); PG8_BAR; PG8_MMA(1, 0, At, B0); PG8_MMA(1, 1, At, B1); PG8_BAR; PG8_SCHED;
	s_add_i32 s24, s62, s28
	v_lshl_add_u64 v[204:205], v[204:205], 0, s[50:51]
	s_mov_b32 m0, s24
	ds_read_b128 v[180:183], v154 offset:49152
	ds_read_b128 v[184:187], v154 offset:50176
	ds_read_b128 v[188:191], v154 offset:51200
	ds_read_b128 v[192:195], v154 offset:52224
	ds_read_b128 v[196:199], v154 offset:53248
	ds_read_b128 v[200:203], v154 offset:54272
	ds_read_b128 v[208:211], v154 offset:55296
	ds_read_b128 v[212:215], v154 offset:56320
	global_load_lds_dwordx4 v[204:205], off
	s_add_i32 m0, s24, 0x2000
	s_add_u32 s22, s22, 0x40080
	v_lshl_add_u64 v[204:205], v[216:217], 0, s[50:51]
	s_addc_u32 s23, s23, 0
	s_add_i32 s24, s67, s28
	global_load_lds_dwordx4 v[204:205], off
	v_lshl_add_u64 v[204:205], s[22:23], 0, v[138:139]
	s_mov_b32 m0, s24
	s_nop 0
	global_load_lds_dwordx4 v[204:205], off
	v_lshl_add_u64 v[204:205], s[22:23], 0, v[134:135]
	s_add_i32 m0, s24, 0x2000
	s_nop 0
	global_load_lds_dwordx4 v[204:205], off
	v_lshl_add_u64 v[204:205], v[218:219], 0, s[50:51]
	s_mov_b32 m0, s35
	s_nop 0
	global_load_lds_dwordx4 v[204:205], off
	v_lshl_add_u64 v[204:205], v[222:223], 0, s[50:51]
	s_mov_b32 m0, s38
	s_nop 0
	global_load_lds_dwordx4 v[204:205], off
	s_waitcnt vmcnt(8)
	s_waitcnt lgkmcnt(0)
	s_barrier
	s_setprio 1
	s_waitcnt lgkmcnt(0)
	v_mfma_f32_16x16x32_bf16 v[94:97], v[130:133], v[180:183], v[94:97]
	v_mfma_f32_16x16x32_bf16 v[90:93], v[156:159], v[180:183], v[90:93]
	v_mfma_f32_16x16x32_bf16 v[86:89], v[130:133], v[188:191], v[86:89]
	v_mfma_f32_16x16x32_bf16 v[82:85], v[156:159], v[188:191], v[82:85]
	v_mfma_f32_16x16x32_bf16 v[78:81], v[130:133], v[196:199], v[78:81]
	v_mfma_f32_16x16x32_bf16 v[74:77], v[156:159], v[196:199], v[74:77]
	v_mfma_f32_16x16x32_bf16 v[70:73], v[130:133], v[208:211], v[70:73]
	v_mfma_f32_16x16x32_bf16 v[66:69], v[156:159], v[208:211], v[66:69]
	v_mfma_f32_16x16x32_bf16 v[94:97], v[148:151], v[184:187], v[94:97]
	v_mfma_f32_16x16x32_bf16 v[90:93], v[160:163], v[184:187], v[90:93]
	v_mfma_f32_16x16x32_bf16 v[86:89], v[148:151], v[192:195], v[86:89]
	v_mfma_f32_16x16x32_bf16 v[82:85], v[160:163], v[192:195], v[82:85]
	v_mfma_f32_16x16x32_bf16 v[78:81], v[148:151], v[200:203], v[78:81]
	v_mfma_f32_16x16x32_bf16 v[74:77], v[160:163], v[200:203], v[74:77]
	v_mfma_f32_16x16x32_bf16 v[70:73], v[148:151], v[212:215], v[70:73]
	v_mfma_f32_16x16x32_bf16 v[66:69], v[160:163], v[212:215], v[66:69]
	s_setprio 0
	s_setprio 1
	v_mfma_f32_16x16x32_bf16 v[28:31], v[164:167], v[180:183], v[28:31]
	v_mfma_f32_16x16x32_bf16 v[24:27], v[172:175], v[180:183], v[24:27]
	v_mfma_f32_16x16x32_bf16 v[20:23], v[164:167], v[188:191], v[20:23]
	v_mfma_f32_16x16x32_bf16 v[16:19], v[172:175], v[188:191], v[16:19]
	v_mfma_f32_16x16x32_bf16 v[12:15], v[164:167], v[196:199], v[12:15]
	v_mfma_f32_16x16x32_bf16 v[8:11], v[172:175], v[196:199], v[8:11]
	v_mfma_f32_16x16x32_bf16 v[4:7], v[164:167], v[208:211], v[4:7]
	v_mfma_f32_16x16x32_bf16 v[0:3], v[172:175], v[208:211], v[0:3]
	v_mfma_f32_16x16x32_bf16 v[28:31], v[168:171], v[184:187], v[28:31]
	v_mfma_f32_16x16x32_bf16 v[24:27], v[176:179], v[184:187], v[24:27]
	v_mfma_f32_16x16x32_bf16 v[20:23], v[168:171], v[192:195], v[20:23]
	v_mfma_f32_16x16x32_bf16 v[16:19], v[176:179], v[192:195], v[16:19]
	v_mfma_f32_16x16x32_bf16 v[12:15], v[168:171], v[200:203], v[12:15]
	v_mfma_f32_16x16x32_bf16 v[8:11], v[176:179], v[200:203], v[8:11]
	v_mfma_f32_16x16x32_bf16 v[4:7], v[168:171], v[212:215], v[4:7]
	v_mfma_f32_16x16x32_bf16 v[0:3], v[176:179], v[212:215], v[0:3]
	s_setprio 0
	s_add_i32 s59, s59, 2
	s_add_u32 s4, s4, 0x100
	s_addc_u32 s5, s5, 0
	s_cmp_gt_u32 s59, 13
	s_barrier
	s_cbranch_scc0 .LBB0_87
	s_and_b64 vcc, exec, s[18:19]
	s_cbranch_vccz .LBB0_90
	s_barrier

; #define PG8_STAGE(bufoff, gbase, voff) do { _Pragma("unroll") for (int _i = 0; _i < 2; ++_i) \
;         __builtin_amdgcn_global_load_lds((const unsigned*)((const char*)(gbase) + (voff)[_i]), (PG8_LAS unsigned*)(lds + (bufoff) + ldsw + _i * 8192), 16, 0, 0); } while (0)
; #define PG8_LDA(dst, b, h) do { _Pragma("unroll") for (int m = 0; m < 4; ++m) _Pragma("unroll") for (int k = 0; k < 2; ++k) dst[m][k] = *(const PG8_LAS bf16x8*)(lds + PG8_SA(b, h) + aoff + m * 2048 + k * 1024); } while (0)
; #define PG8_LDB(dst, b, h) do { _Pragma("unroll") for (int n = 0; n < 2; ++n) _Pragma("unroll") for (int k = 0; k < 2; ++k) dst[n][k] = *(const PG8_LAS bf16x8*)(lds + PG8_SB(b, h) + boff + n * 2048 + k * 1024); } while (0)
; #define PG8_MMA(ai, bj, At, Bt) do { __builtin_amdgcn_s_setprio(1); _Pragma("unroll") for (int m = 0; m < 4; ++m) _Pragma("unroll") for (int n = 0; n < 2; ++n) _Pragma("unroll") for (int k = 0; k < 2; ++k) \
;         acc[ai][bj][m][n] = __builtin_amdgcn_mfma_f32_16x16x32_bf16(Bt[n][k], At[m][k], acc[ai][bj][m][n], 0, 0, 0); __builtin_amdgcn_s_setprio(0); } while (0)
; #define PG8_WAIT_V(n) asm volatile("s_waitcnt vmcnt(" #n ")" ::: "memory")
; #define PG8_BAR __builtin_amdgcn_s_barrier()
; template <class Epi, class Sched, bool ALIGN_EPI = false, bool SP2 = false>
; __device__ __forceinline__ void gemm_phase(PG8_LAS unsigned char* lds, const Gemm g, const Sched& S, const Epi& E) {
;     ...
;         for (int t = 0; t < nt; t += 2) {
;             const bool last = (t == nt - 2);
;             const char* a1 = cA + (size_t)(t + 1) * kstep;
;             const char* a2 = last ? nA : cA + (size_t)(t + 2) * kstep; const char* b2 = last ? nB : cB + (size_t)(t + 2) * kstep;
;             const char* a3 = a2 + kstep; const char* b3 = b2 + kstep;
;             if (last && has_next) S.a_ready(nxt);
;             if constexpr (SP2) {
;             PG8_LDB(B0, 0, 0); PG8_LDB(B1, 0, 1); PG8_SCHED; PG8_LDA(At, 0, 0); PG8_STAGE(PG8_SA(1, 1), a1 + hstepA, voffA);
;             PG8_WAIT_V(8); PG8_WAIT_L(0); PG8_BAR; PG8_MMA(0, 0, At, B0); PG8_MMA(0, 1, At, B1); PG8_BAR; PG8_SCHED;
;             PG8_LDA(At, 0, 1); PG8_STAGE(PG8_SB(0, 0), b2, voffB); PG8_STAGE(PG8_SB(0, 1), b2 + hstepB, voffB); PG8_STAGE(PG8_SA(0, 0), a2, voffA);
;             PG8_WAIT_V(8); PG8_WAIT_L(0); PG8_BAR; PG8_MMA(1, 0, At, B0); PG8_MMA(1, 1, At, B1); PG8_BAR; PG8_SCHED;
.LBB0_476:
	s_add_u32 s21, s88, s24
	s_addc_u32 s28, s89, s25
	s_add_u32 s29, s21, 0x4900100
	s_addc_u32 s28, s28, 0
	s_add_u32 s44, s55, s24
	s_addc_u32 s45, s70, s25
	s_add_i32 s21, 0, 0x10000
	s_cmpk_eq_i32 s24, 0x700
	s_cselect_b32 s53, s97, s28
	s_cselect_b32 s52, s96, s29
	s_cselect_b32 s45, s46, s45
	s_cselect_b32 s44, s54, s44
	s_add_i32 s91, 0, 0x14000
	v_add_u32_e32 v156, s21, v142
	v_add_u32_e32 v172, s91, v142
	ds_read_b128 v[144:147], v156
	ds_read_b128 v[148:151], v156 offset:1024
	ds_read_b128 v[152:155], v156 offset:2048
	ds_read_b128 v[156:159], v156 offset:3072
	ds_read_b128 v[160:163], v172
	ds_read_b128 v[164:167], v172 offset:1024
	ds_read_b128 v[168:171], v172 offset:2048
	ds_read_b128 v[172:175], v172 offset:3072
	v_lshl_add_u64 v[204:205], v[138:139], 0, s[24:25]
	s_add_i32 m0, s27, 0xc000
	ds_read_b128 v[176:179], v143
	ds_read_b128 v[180:183], v143 offset:1024
	ds_read_b128 v[184:187], v143 offset:2048
	ds_read_b128 v[188:191], v143 offset:3072
	ds_read_b128 v[192:195], v143 offset:4096
	ds_read_b128 v[196:199], v143 offset:5120
	ds_read_b128 v[200:203], v143 offset:6144
	ds_read_b128 v[208:211], v143 offset:7168
	global_load_lds_dwordx4 v[204:205], off
	v_lshl_add_u64 v[204:205], v[140:141], 0, s[24:25]
	s_add_i32 m0, s27, 0xe000
	s_nop 0
	global_load_lds_dwordx4 v[204:205], off
	s_waitcnt vmcnt(8)
	s_waitcnt lgkmcnt(0)
	s_barrier
	s_setprio 1
	s_waitcnt lgkmcnt(0)
	v_mfma_f32_16x16x32_bf16 v[126:129], v[144:147], v[176:179], v[126:129]
	v_mfma_f32_16x16x32_bf16 v[122:125], v[152:155], v[176:179], v[122:125]
	v_mfma_f32_16x16x32_bf16 v[110:113], v[144:147], v[184:187], v[110:113]
	v_mfma_f32_16x16x32_bf16 v[106:109], v[152:155], v[184:187], v[106:109]
	v_mfma_f32_16x16x32_bf16 v[94:97], v[144:147], v[192:195], v[94:97]
	v_mfma_f32_16x16x32_bf16 v[90:93], v[152:155], v[192:195], v[90:93]
	v_mfma_f32_16x16x32_bf16 v[78:81], v[144:147], v[200:203], v[78:81]
	v_mfma_f32_16x16x32_bf16 v[74:77], v[152:155], v[200:203], v[74:77]
	v_mfma_f32_16x16x32_bf16 v[126:129], v[148:151], v[180:183], v[126:129]
	v_mfma_f32_16x16x32_bf16 v[122:125], v[156:159], v[180:183], v[122:125]
	v_mfma_f32_16x16x32_bf16 v[110:113], v[148:151], v[188:191], v[110:113]
	v_mfma_f32_16x16x32_bf16 v[106:109], v[156:159], v[188:191], v[106:109]
	v_mfma_f32_16x16x32_bf16 v[94:97], v[148:151], v[196:199], v[94:97]
	v_mfma_f32_16x16x32_bf16 v[90:93], v[156:159], v[196:199], v[90:93]
	v_mfma_f32_16x16x32_bf16 v[78:81], v[148:151], v[208:211], v[78:81]
	v_mfma_f32_16x16x32_bf16 v[74:77], v[156:159], v[208:211], v[74:77]
	s_setprio 0
	s_setprio 1
	v_mfma_f32_16x16x32_bf16 v[118:121], v[160:163], v[176:179], v[118:121]
	v_mfma_f32_16x16x32_bf16 v[114:117], v[168:171], v[176:179], v[114:117]
	v_mfma_f32_16x16x32_bf16 v[102:105], v[160:163], v[184:187], v[102:105]
	v_mfma_f32_16x16x32_bf16 v[98:101], v[168:171], v[184:187], v[98:101]
	v_mfma_f32_16x16x32_bf16 v[86:89], v[160:163], v[192:195], v[86:89]
	v_mfma_f32_16x16x32_bf16 v[82:85], v[168:171], v[192:195], v[82:85]
	v_mfma_f32_16x16x32_bf16 v[70:73], v[160:163], v[200:203], v[70:73]
	v_mfma_f32_16x16x32_bf16 v[66:69], v[168:171], v[200:203], v[66:69]
	v_mfma_f32_16x16x32_bf16 v[118:121], v[164:167], v[180:183], v[118:121]
	v_mfma_f32_16x16x32_bf16 v[114:117], v[172:175], v[180:183], v[114:117]
	v_mfma_f32_16x16x32_bf16 v[102:105], v[164:167], v[188:191], v[102:105]
	v_mfma_f32_16x16x32_bf16 v[98:101], v[172:175], v[188:191], v[98:101]
	v_mfma_f32_16x16x32_bf16 v[86:89], v[164:167], v[196:199], v[86:89]
	v_mfma_f32_16x16x32_bf16 v[82:85], v[172:175], v[196:199], v[82:85]
	v_mfma_f32_16x16x32_bf16 v[70:73], v[164:167], v[208:211], v[70:73]
	v_mfma_f32_16x16x32_bf16 v[66:69], v[172:175], v[208:211], v[66:69]
	s_setprio 0
	s_barrier
	s_add_i32 s28, s21, s26
	v_lshl_add_u64 v[204:205], s[44:45], 0, v[64:65]
	s_mov_b32 m0, s28
	ds_read_b128 v[176:179], v143 offset:16384
	ds_read_b128 v[180:183], v143 offset:17408
	ds_read_b128 v[184:187], v143 offset:18432
	ds_read_b128 v[188:191], v143 offset:19456
	ds_read_b128 v[192:195], v143 offset:20480
	ds_read_b128 v[196:199], v143 offset:21504
	ds_read_b128 v[200:203], v143 offset:22528
	ds_read_b128 v[208:211], v143 offset:23552
	global_load_lds_dwordx4 v[204:205], off
	s_add_i32 m0, s28, 0x2000
	s_add_u32 s28, s44, 0x40000
	v_lshl_add_u64 v[212:213], s[44:45], 0, v[130:131]
	s_addc_u32 s29, s45, 0
	s_add_i32 s72, s91, s26
	global_load_lds_dwordx4 v[212:213], off
	v_lshl_add_u64 v[214:215], s[28:29], 0, v[64:65]
	s_mov_b32 m0, s72
	v_lshl_add_u64 v[216:217], s[52:53], 0, v[132:133]
	global_load_lds_dwordx4 v[214:215], off
	v_lshl_add_u64 v[214:215], s[28:29], 0, v[130:131]
	s_add_i32 m0, s72, 0x2000
	s_nop 0
	global_load_lds_dwordx4 v[214:215], off
	v_lshl_add_u64 v[214:215], s[52:53], 0, v[134:135]
	s_mov_b32 m0, s27
	s_nop 0
	global_load_lds_dwordx4 v[214:215], off
	s_mov_b32 m0, s34
	s_nop 0
	global_load_lds_dwordx4 v[216:217], off
	s_waitcnt vmcnt(8)
	s_waitcnt lgkmcnt(0)
	s_barrier
; #define PG8_STAGE(bufoff, gbase, voff) do { _Pragma("unroll") for (int _i = 0; _i < 2; ++_i) \
;         __builtin_amdgcn_global_load_lds((const unsigned*)((const char*)(gbase) + (voff)[_i]), (PG8_LAS unsigned*)(lds + (bufoff) + ldsw + _i * 8192), 16, 0, 0); } while (0)
; #define PG8_LDA(dst, b, h) do { _Pragma("unroll") for (int m = 0; m < 4; ++m) _Pragma("unroll") for (int k = 0; k < 2; ++k) dst[m][k] = *(const PG8_LAS bf16x8*)(lds + PG8_SA(b, h) + aoff + m * 2048 + k * 1024); } while (0)
; #define PG8_LDB(dst, b, h) do { _Pragma("unroll") for (int n = 0; n < 2; ++n) _Pragma("unroll") for (int k = 0; k < 2; ++k) dst[n][k] = *(const PG8_LAS bf16x8*)(lds + PG8_SB(b, h) + boff + n * 2048 + k * 1024); } while (0)
; #define PG8_MMA(ai, bj, At, Bt) do { __builtin_amdgcn_s_setprio(1); _Pragma("unroll") for (int m = 0; m < 4; ++m) _Pragma("unroll") for (int n = 0; n < 2; ++n) _Pragma("unroll") for (int k = 0; k < 2; ++k) \
;         acc[ai][bj][m][n] = __builtin_amdgcn_mfma_f32_16x16x32_bf16(Bt[n][k], At[m][k], acc[ai][bj][m][n], 0, 0, 0); __builtin_amdgcn_s_setprio(0); } while (0)
; #define PG8_WAIT_V(n) asm volatile("s_waitcnt vmcnt(" #n ")" ::: "memory")
; #define PG8_WAIT_L(n) asm volatile("s_waitcnt lgkmcnt(" #n ")" ::: "memory")
; #define PG8_BAR __builtin_amdgcn_s_barrier()
; #define PG8_SCHED __builtin_amdgcn_sched_barrier(0)
; template <class Epi, class Sched, bool ALIGN_EPI = false, bool SP2 = false>
; __device__ __forceinline__ void gemm_phase(PG8_LAS unsigned char* lds, const Gemm g, const Sched& S, const Epi& E) {
;     ...
;             PG8_WAIT_V(8); PG8_WAIT_L(0); PG8_BAR; PG8_MMA(1, 0, At, B0); PG8_MMA(1, 1, At, B1); PG8_BAR; PG8_SCHED;
;             PG8_LDB(B0, 1, 0); PG8_LDB(B1, 1, 1); PG8_SCHED; PG8_LDA(At, 1, 0); PG8_STAGE(PG8_SA(0, 1), a2 + hstepA, voffA);
;             PG8_WAIT_V(8); PG8_WAIT_L(0); PG8_BAR; PG8_MMA(0, 0, At, B0); PG8_MMA(0, 1, At, B1); PG8_BAR; PG8_SCHED;
	s_setprio 1
	s_waitcnt lgkmcnt(0)
	v_mfma_f32_16x16x32_bf16 v[60:63], v[144:147], v[176:179], v[60:63]
	v_mfma_f32_16x16x32_bf16 v[56:59], v[152:155], v[176:179], v[56:59]
	v_mfma_f32_16x16x32_bf16 v[44:47], v[144:147], v[184:187], v[44:47]
	v_mfma_f32_16x16x32_bf16 v[40:43], v[152:155], v[184:187], v[40:43]
	v_mfma_f32_16x16x32_bf16 v[28:31], v[144:147], v[192:195], v[28:31]
	v_mfma_f32_16x16x32_bf16 v[24:27], v[152:155], v[192:195], v[24:27]
	v_mfma_f32_16x16x32_bf16 v[12:15], v[144:147], v[200:203], v[12:15]
	v_mfma_f32_16x16x32_bf16 v[8:11], v[152:155], v[200:203], v[8:11]
	v_mfma_f32_16x16x32_bf16 v[60:63], v[148:151], v[180:183], v[60:63]
	v_mfma_f32_16x16x32_bf16 v[56:59], v[156:159], v[180:183], v[56:59]
	v_mfma_f32_16x16x32_bf16 v[44:47], v[148:151], v[188:191], v[44:47]
	v_mfma_f32_16x16x32_bf16 v[40:43], v[156:159], v[188:191], v[40:43]
	v_mfma_f32_16x16x32_bf16 v[28:31], v[148:151], v[196:199], v[28:31]
	v_mfma_f32_16x16x32_bf16 v[24:27], v[156:159], v[196:199], v[24:27]
	v_mfma_f32_16x16x32_bf16 v[12:15], v[148:151], v[208:211], v[12:15]
	v_mfma_f32_16x16x32_bf16 v[8:11], v[156:159], v[208:211], v[8:11]
	s_setprio 0
	s_setprio 1
	v_mfma_f32_16x16x32_bf16 v[52:55], v[160:163], v[176:179], v[52:55]
	v_mfma_f32_16x16x32_bf16 v[48:51], v[168:171], v[176:179], v[48:51]
	v_mfma_f32_16x16x32_bf16 v[36:39], v[160:163], v[184:187], v[36:39]
	v_mfma_f32_16x16x32_bf16 v[32:35], v[168:171], v[184:187], v[32:35]
	v_mfma_f32_16x16x32_bf16 v[20:23], v[160:163], v[192:195], v[20:23]
	v_mfma_f32_16x16x32_bf16 v[16:19], v[168:171], v[192:195], v[16:19]
	v_mfma_f32_16x16x32_bf16 v[4:7], v[160:163], v[200:203], v[4:7]
	v_mfma_f32_16x16x32_bf16 v[0:3], v[168:171], v[200:203], v[0:3]
	v_mfma_f32_16x16x32_bf16 v[52:55], v[164:167], v[180:183], v[52:55]
	v_mfma_f32_16x16x32_bf16 v[48:51], v[172:175], v[180:183], v[48:51]
	v_mfma_f32_16x16x32_bf16 v[36:39], v[164:167], v[188:191], v[36:39]
	v_mfma_f32_16x16x32_bf16 v[32:35], v[172:175], v[188:191], v[32:35]
	v_mfma_f32_16x16x32_bf16 v[20:23], v[164:167], v[196:199], v[20:23]
	v_mfma_f32_16x16x32_bf16 v[16:19], v[172:175], v[196:199], v[16:19]
	v_mfma_f32_16x16x32_bf16 v[4:7], v[164:167], v[208:211], v[4:7]
	v_mfma_f32_16x16x32_bf16 v[0:3], v[172:175], v[208:211], v[0:3]
	s_setprio 0
	s_barrier
	s_add_i32 s28, 0, 0x18000
	s_add_i32 s29, 0, 0x1c000
	v_add_u32_e32 v156, s28, v142
	v_add_u32_e32 v172, s29, v142
	ds_read_b128 v[144:147], v156
	ds_read_b128 v[148:151], v156 offset:1024
	ds_read_b128 v[152:155], v156 offset:2048
	ds_read_b128 v[156:159], v156 offset:3072
	ds_read_b128 v[160:163], v172
	ds_read_b128 v[164:167], v172 offset:1024
	ds_read_b128 v[168:171], v172 offset:2048
	ds_read_b128 v[172:175], v172 offset:3072
	s_add_u32 s52, s52, 0x40000
	s_addc_u32 s53, s53, 0
	s_mov_b32 m0, s35
	v_lshl_add_u64 v[218:219], s[52:53], 0, v[134:135]
	ds_read_b128 v[176:179], v143 offset:32768
	ds_read_b128 v[180:183], v143 offset:33792
	ds_read_b128 v[184:187], v143 offset:34816
	ds_read_b128 v[188:191], v143 offset:35840
	ds_read_b128 v[192:195], v143 offset:36864
	ds_read_b128 v[196:199], v143 offset:37888
	ds_read_b128 v[200:203], v143 offset:38912
	ds_read_b128 v[208:211], v143 offset:39936
	global_load_lds_dwordx4 v[218:219], off
	v_lshl_add_u64 v[218:219], s[52:53], 0, v[132:133]
	s_mov_b32 m0, s59
	s_nop 0
	global_load_lds_dwordx4 v[218:219], off
	s_waitcnt vmcnt(8)
	s_waitcnt lgkmcnt(0)
	s_barrier
	s_setprio 1
	s_waitcnt lgkmcnt(0)
	v_mfma_f32_16x16x32_bf16 v[126:129], v[144:147], v[176:179], v[126:129]
	v_mfma_f32_16x16x32_bf16 v[122:125], v[152:155], v[176:179], v[122:125]
	v_mfma_f32_16x16x32_bf16 v[110:113], v[144:147], v[184:187], v[110:113]
	v_mfma_f32_16x16x32_bf16 v[106:109], v[152:155], v[184:187], v[106:109]
	v_mfma_f32_16x16x32_bf16 v[94:97], v[144:147], v[192:195], v[94:97]
	v_mfma_f32_16x16x32_bf16 v[90:93], v[152:155], v[192:195], v[90:93]
	v_mfma_f32_16x16x32_bf16 v[78:81], v[144:147], v[200:203], v[78:81]
	v_mfma_f32_16x16x32_bf16 v[74:77], v[152:155], v[200:203], v[74:77]
	v_mfma_f32_16x16x32_bf16 v[126:129], v[148:151], v[180:183], v[126:129]
	v_mfma_f32_16x16x32_bf16 v[122:125], v[156:159], v[180:183], v[122:125]
	v_mfma_f32_16x16x32_bf16 v[110:113], v[148:151], v[188:191], v[110:113]
	v_mfma_f32_16x16x32_bf16 v[106:109], v[156:159], v[188:191], v[106:109]
	v_mfma_f32_16x16x32_bf16 v[94:97], v[148:151], v[196:199], v[94:97]
	v_mfma_f32_16x16x32_bf16 v[90:93], v[156:159], v[196:199], v[90:93]
	v_mfma_f32_16x16x32_bf16 v[78:81], v[148:151], v[208:211], v[78:81]
	v_mfma_f32_16x16x32_bf16 v[74:77], v[156:159], v[208:211], v[74:77]
	s_setprio 0
	s_setprio 1
	v_mfma_f32_16x16x32_bf16 v[118:121], v[160:163], v[176:179], v[118:121]
	v_mfma_f32_16x16x32_bf16 v[114:117], v[168:171], v[176:179], v[114:117]
	v_mfma_f32_16x16x32_bf16 v[102:105], v[160:163], v[184:187], v[102:105]
	v_mfma_f32_16x16x32_bf16 v[98:101], v[168:171], v[184:187], v[98:101]
	v_mfma_f32_16x16x32_bf16 v[86:89], v[160:163], v[192:195], v[86:89]
	v_mfma_f32_16x16x32_bf16 v[82:85], v[168:171], v[192:195], v[82:85]
	v_mfma_f32_16x16x32_bf16 v[70:73], v[160:163], v[200:203], v[70:73]
	v_mfma_f32_16x16x32_bf16 v[66:69], v[168:171], v[200:203], v[66:69]
	v_mfma_f32_16x16x32_bf16 v[118:121], v[164:167], v[180:183], v[118:121]
	v_mfma_f32_16x16x32_bf16 v[114:117], v[172:175], v[180:183], v[114:117]
	v_mfma_f32_16x16x32_bf16 v[102:105], v[164:167], v[188:191], v[102:105]
	v_mfma_f32_16x16x32_bf16 v[98:101], v[172:175], v[188:191], v[98:101]
	v_mfma_f32_16x16x32_bf16 v[86:89], v[164:167], v[196:199], v[86:89]
	v_mfma_f32_16x16x32_bf16 v[82:85], v[172:175], v[196:199], v[82:85]
	v_mfma_f32_16x16x32_bf16 v[70:73], v[164:167], v[208:211], v[70:73]
	v_mfma_f32_16x16x32_bf16 v[66:69], v[172:175], v[208:211], v[66:69]
	s_setprio 0
	s_barrier
; #define PG8_STAGE(bufoff, gbase, voff) do { _Pragma("unroll") for (int _i = 0; _i < 2; ++_i) \
;         __builtin_amdgcn_global_load_lds((const unsigned*)((const char*)(gbase) + (voff)[_i]), (PG8_LAS unsigned*)(lds + (bufoff) + ldsw + _i * 8192), 16, 0, 0); } while (0)
; #define PG8_LDA(dst, b, h) do { _Pragma("unroll") for (int m = 0; m < 4; ++m) _Pragma("unroll") for (int k = 0; k < 2; ++k) dst[m][k] = *(const PG8_LAS bf16x8*)(lds + PG8_SA(b, h) + aoff + m * 2048 + k * 1024); } while (0)
; #define PG8_MMA(ai, bj, At, Bt) do { __builtin_amdgcn_s_setprio(1); _Pragma("unroll") for (int m = 0; m < 4; ++m) _Pragma("unroll") for (int n = 0; n < 2; ++n) _Pragma("unroll") for (int k = 0; k < 2; ++k) \
;         acc[ai][bj][m][n] = __builtin_amdgcn_mfma_f32_16x16x32_bf16(Bt[n][k], At[m][k], acc[ai][bj][m][n], 0, 0, 0); __builtin_amdgcn_s_setprio(0); } while (0)
; #define PG8_WAIT_V(n) asm volatile("s_waitcnt vmcnt(" #n ")" ::: "memory")
; #define PG8_WAIT_L(n) asm volatile("s_waitcnt lgkmcnt(" #n ")" ::: "memory")
; #define PG8_BAR __builtin_amdgcn_s_barrier()
; #define PG8_SCHED __builtin_amdgcn_sched_barrier(0)
; template <class Epi, class Sched, bool ALIGN_EPI = false, bool SP2 = false>
; __device__ __forceinline__ void gemm_phase(PG8_LAS unsigned char* lds, const Gemm g, const Sched& S, const Epi& E) {
;     ...
;         for (int t = 0; t < nt; t += 2) {
;             const bool last = (t == nt - 2);
;     ...
;             PG8_LDA(At, 1, 1); PG8_STAGE(PG8_SB(1, 0), b3, voffB); PG8_STAGE(PG8_SB(1, 1), b3 + hstepB, voffB); PG8_STAGE(PG8_SA(1, 0), a3, voffA);
;             PG8_WAIT_V(8); PG8_WAIT_L(0); PG8_BAR; PG8_MMA(1, 0, At, B0); PG8_MMA(1, 1, At, B1); PG8_BAR; PG8_SCHED;
	s_add_i32 s52, s28, s26
	v_lshl_add_u64 v[204:205], v[204:205], 0, s[50:51]
	s_mov_b32 m0, s52
	ds_read_b128 v[176:179], v143 offset:49152
	ds_read_b128 v[180:183], v143 offset:50176
	ds_read_b128 v[184:187], v143 offset:51200
	ds_read_b128 v[188:191], v143 offset:52224
	ds_read_b128 v[192:195], v143 offset:53248
	ds_read_b128 v[196:199], v143 offset:54272
	ds_read_b128 v[200:203], v143 offset:55296
	ds_read_b128 v[208:211], v143 offset:56320
	global_load_lds_dwordx4 v[204:205], off
	s_add_i32 m0, s52, 0x2000
	s_add_u32 s44, s44, 0x40080
	v_lshl_add_u64 v[204:205], v[212:213], 0, s[50:51]
	s_addc_u32 s45, s45, 0
	s_add_i32 s52, s29, s26
	global_load_lds_dwordx4 v[204:205], off
	v_lshl_add_u64 v[204:205], s[44:45], 0, v[64:65]
	s_mov_b32 m0, s52
	s_nop 0
	global_load_lds_dwordx4 v[204:205], off
	v_lshl_add_u64 v[204:205], s[44:45], 0, v[130:131]
	s_add_i32 m0, s52, 0x2000
	s_nop 0
	global_load_lds_dwordx4 v[204:205], off
	v_lshl_add_u64 v[204:205], v[214:215], 0, s[50:51]
	s_mov_b32 m0, s67
	s_nop 0
	global_load_lds_dwordx4 v[204:205], off
	v_lshl_add_u64 v[204:205], v[216:217], 0, s[50:51]
	s_mov_b32 m0, s69
	s_nop 0
	global_load_lds_dwordx4 v[204:205], off
	s_waitcnt vmcnt(8)
	s_waitcnt lgkmcnt(0)
	s_barrier
	s_setprio 1
	s_waitcnt lgkmcnt(0)
	v_mfma_f32_16x16x32_bf16 v[60:63], v[144:147], v[176:179], v[60:63]
	v_mfma_f32_16x16x32_bf16 v[56:59], v[152:155], v[176:179], v[56:59]
	v_mfma_f32_16x16x32_bf16 v[44:47], v[144:147], v[184:187], v[44:47]
	v_mfma_f32_16x16x32_bf16 v[40:43], v[152:155], v[184:187], v[40:43]
	v_mfma_f32_16x16x32_bf16 v[28:31], v[144:147], v[192:195], v[28:31]
	v_mfma_f32_16x16x32_bf16 v[24:27], v[152:155], v[192:195], v[24:27]
	v_mfma_f32_16x16x32_bf16 v[12:15], v[144:147], v[200:203], v[12:15]
	v_mfma_f32_16x16x32_bf16 v[8:11], v[152:155], v[200:203], v[8:11]
	v_mfma_f32_16x16x32_bf16 v[60:63], v[148:151], v[180:183], v[60:63]
	v_mfma_f32_16x16x32_bf16 v[56:59], v[156:159], v[180:183], v[56:59]
	v_mfma_f32_16x16x32_bf16 v[44:47], v[148:151], v[188:191], v[44:47]
	v_mfma_f32_16x16x32_bf16 v[40:43], v[156:159], v[188:191], v[40:43]
	v_mfma_f32_16x16x32_bf16 v[28:31], v[148:151], v[196:199], v[28:31]
	v_mfma_f32_16x16x32_bf16 v[24:27], v[156:159], v[196:199], v[24:27]
	v_mfma_f32_16x16x32_bf16 v[12:15], v[148:151], v[208:211], v[12:15]
	v_mfma_f32_16x16x32_bf16 v[8:11], v[156:159], v[208:211], v[8:11]
	s_setprio 0
	s_setprio 1
	v_mfma_f32_16x16x32_bf16 v[52:55], v[160:163], v[176:179], v[52:55]
	v_mfma_f32_16x16x32_bf16 v[48:51], v[168:171], v[176:179], v[48:51]
	v_mfma_f32_16x16x32_bf16 v[36:39], v[160:163], v[184:187], v[36:39]
	v_mfma_f32_16x16x32_bf16 v[32:35], v[168:171], v[184:187], v[32:35]
	v_mfma_f32_16x16x32_bf16 v[20:23], v[160:163], v[192:195], v[20:23]
	v_mfma_f32_16x16x32_bf16 v[16:19], v[168:171], v[192:195], v[16:19]
	v_mfma_f32_16x16x32_bf16 v[4:7], v[160:163], v[200:203], v[4:7]
	v_mfma_f32_16x16x32_bf16 v[0:3], v[168:171], v[200:203], v[0:3]
	v_mfma_f32_16x16x32_bf16 v[52:55], v[164:167], v[180:183], v[52:55]
	v_mfma_f32_16x16x32_bf16 v[48:51], v[172:175], v[180:183], v[48:51]
	v_mfma_f32_16x16x32_bf16 v[36:39], v[164:167], v[188:191], v[36:39]
	v_mfma_f32_16x16x32_bf16 v[32:35], v[172:175], v[188:191], v[32:35]
	v_mfma_f32_16x16x32_bf16 v[20:23], v[164:167], v[196:199], v[20:23]
	v_mfma_f32_16x16x32_bf16 v[16:19], v[172:175], v[196:199], v[16:19]
	v_mfma_f32_16x16x32_bf16 v[4:7], v[164:167], v[208:211], v[4:7]
	v_mfma_f32_16x16x32_bf16 v[0:3], v[172:175], v[208:211], v[0:3]
	s_setprio 0
	s_add_i32 s71, s71, 2
	s_add_u32 s24, s24, 0x100
	s_addc_u32 s25, s25, 0
	s_cmp_gt_u32 s71, 13
	s_barrier
	s_cbranch_scc0 .LBB0_476
	s_and_b64 vcc, exec, s[12:13]
	s_cbranch_vccz .LBB0_479
	s_barrier

; #define PG8_STAGE(bufoff, gbase, voff) do { _Pragma("unroll") for (int _i = 0; _i < 2; ++_i) \
;         __builtin_amdgcn_global_load_lds((const unsigned*)((const char*)(gbase) + (voff)[_i]), (PG8_LAS unsigned*)(lds + (bufoff) + ldsw + _i * 8192), 16, 0, 0); } while (0)
; #define PG8_LDA(dst, b, h) do { _Pragma("unroll") for (int m = 0; m < 4; ++m) _Pragma("unroll") for (int k = 0; k < 2; ++k) dst[m][k] = *(const PG8_LAS bf16x8*)(lds + PG8_SA(b, h) + aoff + m * 2048 + k * 1024); } while (0)
; #define PG8_LDB(dst, b, h) do { _Pragma("unroll") for (int n = 0; n < 2; ++n) _Pragma("unroll") for (int k = 0; k < 2; ++k) dst[n][k] = *(const PG8_LAS bf16x8*)(lds + PG8_SB(b, h) + boff + n * 2048 + k * 1024); } while (0)
; #define PG8_MMA(ai, bj, At, Bt) do { __builtin_amdgcn_s_setprio(1); _Pragma("unroll") for (int m = 0; m < 4; ++m) _Pragma("unroll") for (int n = 0; n < 2; ++n) _Pragma("unroll") for (int k = 0; k < 2; ++k) \
;         acc[ai][bj][m][n] = __builtin_amdgcn_mfma_f32_16x16x32_bf16(Bt[n][k], At[m][k], acc[ai][bj][m][n], 0, 0, 0); __builtin_amdgcn_s_setprio(0); } while (0)
; #define PG8_WAIT_V(n) asm volatile("s_waitcnt vmcnt(" #n ")" ::: "memory")
; #define PG8_BAR __builtin_amdgcn_s_barrier()
; template <class Epi, class Sched, bool ALIGN_EPI = false, bool SP2 = false>
; __device__ __forceinline__ void gemm_phase(PG8_LAS unsigned char* lds, const Gemm g, const Sched& S, const Epi& E) {
;     ...
;         for (int t = 0; t < nt; t += 2) {
;             const bool last = (t == nt - 2);
;             const char* a1 = cA + (size_t)(t + 1) * kstep;
;             const char* a2 = last ? nA : cA + (size_t)(t + 2) * kstep; const char* b2 = last ? nB : cB + (size_t)(t + 2) * kstep;
;             const char* a3 = a2 + kstep; const char* b3 = b2 + kstep;
;             if (last && has_next) S.a_ready(nxt);
;             if constexpr (SP2) {
;             PG8_LDB(B0, 0, 0); PG8_LDB(B1, 0, 1); PG8_SCHED; PG8_LDA(At, 0, 0); PG8_STAGE(PG8_SA(1, 1), a1 + hstepA, voffA);
;             PG8_WAIT_V(8); PG8_WAIT_L(0); PG8_BAR; PG8_MMA(0, 0, At, B0); PG8_MMA(0, 1, At, B1); PG8_BAR; PG8_SCHED;
;             PG8_LDA(At, 0, 1); PG8_STAGE(PG8_SB(0, 0), b2, voffB); PG8_STAGE(PG8_SB(0, 1), b2 + hstepB, voffB); PG8_STAGE(PG8_SA(0, 0), a2, voffA);
;             PG8_WAIT_V(8); PG8_WAIT_L(0); PG8_BAR; PG8_MMA(1, 0, At, B0); PG8_MMA(1, 1, At, B1); PG8_BAR; PG8_SCHED;
.LBB0_488:
	v_add_u32_e32 v142, s21, v212
	v_add_u32_e32 v158, s91, v212
	ds_read_b128 v[130:133], v142
	ds_read_b128 v[134:137], v142 offset:1024
	ds_read_b128 v[138:141], v142 offset:2048
	ds_read_b128 v[142:145], v142 offset:3072
	ds_read_b128 v[146:149], v158
	ds_read_b128 v[150:153], v158 offset:1024
	ds_read_b128 v[154:157], v158 offset:2048
	ds_read_b128 v[158:161], v158 offset:3072
	s_add_u32 s26, s0, 0xfffa0080
	s_addc_u32 s27, s1, -1
	s_cmp_eq_u32 s71, 4
	s_cselect_b32 s27, s53, s27
	s_cselect_b32 s26, s52, s26
	s_cselect_b32 vcc_hi, s46, s70
	s_cselect_b32 vcc_lo, s54, s55
	v_lshl_add_u64 v[208:209], s[0:1], 0, v[202:203]
	s_add_i32 m0, s69, 0xc000
	ds_read_b128 v[162:165], v213
	ds_read_b128 v[166:169], v213 offset:1024
	ds_read_b128 v[170:173], v213 offset:2048
	ds_read_b128 v[174:177], v213 offset:3072
	ds_read_b128 v[178:181], v213 offset:4096
	ds_read_b128 v[182:185], v213 offset:5120
	ds_read_b128 v[186:189], v213 offset:6144
	ds_read_b128 v[190:193], v213 offset:7168
	global_load_lds_dwordx4 v[208:209], off
	v_lshl_add_u64 v[208:209], s[0:1], 0, v[204:205]
	s_add_i32 m0, s69, 0xe000
	s_nop 0
	global_load_lds_dwordx4 v[208:209], off
	s_waitcnt vmcnt(8)
	s_waitcnt lgkmcnt(0)
	s_barrier
	s_setprio 1
	s_waitcnt lgkmcnt(0)
	v_mfma_f32_16x16x32_bf16 v[126:129], v[130:133], v[162:165], v[126:129]
	v_mfma_f32_16x16x32_bf16 v[122:125], v[138:141], v[162:165], v[122:125]
	v_mfma_f32_16x16x32_bf16 v[114:117], v[130:133], v[170:173], v[114:117]
	v_mfma_f32_16x16x32_bf16 v[106:109], v[138:141], v[170:173], v[106:109]
	v_mfma_f32_16x16x32_bf16 v[98:101], v[130:133], v[178:181], v[98:101]
	v_mfma_f32_16x16x32_bf16 v[90:93], v[138:141], v[178:181], v[90:93]
	v_mfma_f32_16x16x32_bf16 v[82:85], v[130:133], v[186:189], v[82:85]
	v_mfma_f32_16x16x32_bf16 v[74:77], v[138:141], v[186:189], v[74:77]
	v_mfma_f32_16x16x32_bf16 v[126:129], v[134:137], v[166:169], v[126:129]
	v_mfma_f32_16x16x32_bf16 v[122:125], v[142:145], v[166:169], v[122:125]
	v_mfma_f32_16x16x32_bf16 v[114:117], v[134:137], v[174:177], v[114:117]
	v_mfma_f32_16x16x32_bf16 v[106:109], v[142:145], v[174:177], v[106:109]
	v_mfma_f32_16x16x32_bf16 v[98:101], v[134:137], v[182:185], v[98:101]
	v_mfma_f32_16x16x32_bf16 v[90:93], v[142:145], v[182:185], v[90:93]
	v_mfma_f32_16x16x32_bf16 v[82:85], v[134:137], v[190:193], v[82:85]
	v_mfma_f32_16x16x32_bf16 v[74:77], v[142:145], v[190:193], v[74:77]
	s_setprio 0
	s_setprio 1
	v_mfma_f32_16x16x32_bf16 v[118:121], v[146:149], v[162:165], v[118:121]
	v_mfma_f32_16x16x32_bf16 v[110:113], v[154:157], v[162:165], v[110:113]
	v_mfma_f32_16x16x32_bf16 v[102:105], v[146:149], v[170:173], v[102:105]
	v_mfma_f32_16x16x32_bf16 v[94:97], v[154:157], v[170:173], v[94:97]
	v_mfma_f32_16x16x32_bf16 v[86:89], v[146:149], v[178:181], v[86:89]
	v_mfma_f32_16x16x32_bf16 v[78:81], v[154:157], v[178:181], v[78:81]
	v_mfma_f32_16x16x32_bf16 v[70:73], v[146:149], v[186:189], v[70:73]
	v_mfma_f32_16x16x32_bf16 v[66:69], v[154:157], v[186:189], v[66:69]
	v_mfma_f32_16x16x32_bf16 v[118:121], v[150:153], v[166:169], v[118:121]
	v_mfma_f32_16x16x32_bf16 v[110:113], v[158:161], v[166:169], v[110:113]
	v_mfma_f32_16x16x32_bf16 v[102:105], v[150:153], v[174:177], v[102:105]
	v_mfma_f32_16x16x32_bf16 v[94:97], v[158:161], v[174:177], v[94:97]
	v_mfma_f32_16x16x32_bf16 v[86:89], v[150:153], v[182:185], v[86:89]
	v_mfma_f32_16x16x32_bf16 v[78:81], v[158:161], v[182:185], v[78:81]
	v_mfma_f32_16x16x32_bf16 v[70:73], v[150:153], v[190:193], v[70:73]
	v_mfma_f32_16x16x32_bf16 v[66:69], v[158:161], v[190:193], v[66:69]
	s_setprio 0
	s_barrier
	s_add_i32 s72, s21, s67
	v_lshl_add_u64 v[208:209], vcc, 0, v[64:65]
	s_mov_b32 m0, s72
	ds_read_b128 v[162:165], v213 offset:16384
	ds_read_b128 v[166:169], v213 offset:17408
	ds_read_b128 v[170:173], v213 offset:18432
	ds_read_b128 v[174:177], v213 offset:19456
	ds_read_b128 v[178:181], v213 offset:20480
	ds_read_b128 v[182:185], v213 offset:21504
	ds_read_b128 v[186:189], v213 offset:22528
	ds_read_b128 v[190:193], v213 offset:23552
	global_load_lds_dwordx4 v[208:209], off
	s_add_i32 m0, s72, 0x2000
	s_add_u32 s72, vcc_lo, 0x20000
	v_lshl_add_u64 v[210:211], vcc, 0, v[194:195]
	s_addc_u32 s73, vcc_hi, 0
	s_add_i32 s74, s91, s67
	global_load_lds_dwordx4 v[210:211], off
	v_lshl_add_u64 v[214:215], s[72:73], 0, v[64:65]
	s_mov_b32 m0, s74
	v_lshl_add_u64 v[216:217], s[26:27], 0, v[196:197]
	global_load_lds_dwordx4 v[214:215], off
	v_lshl_add_u64 v[214:215], s[72:73], 0, v[194:195]
	s_add_i32 m0, s74, 0x2000
	s_nop 0
	global_load_lds_dwordx4 v[214:215], off
	v_lshl_add_u64 v[214:215], s[26:27], 0, v[198:199]
	s_mov_b32 m0, s69
	s_nop 0
	global_load_lds_dwordx4 v[214:215], off
	s_mov_b32 m0, s59
	s_nop 0
	global_load_lds_dwordx4 v[216:217], off
	s_waitcnt vmcnt(8)
	s_waitcnt lgkmcnt(0)
	s_barrier
; #define PG8_STAGE(bufoff, gbase, voff) do { _Pragma("unroll") for (int _i = 0; _i < 2; ++_i) \
;         __builtin_amdgcn_global_load_lds((const unsigned*)((const char*)(gbase) + (voff)[_i]), (PG8_LAS unsigned*)(lds + (bufoff) + ldsw + _i * 8192), 16, 0, 0); } while (0)
; #define PG8_LDA(dst, b, h) do { _Pragma("unroll") for (int m = 0; m < 4; ++m) _Pragma("unroll") for (int k = 0; k < 2; ++k) dst[m][k] = *(const PG8_LAS bf16x8*)(lds + PG8_SA(b, h) + aoff + m * 2048 + k * 1024); } while (0)
; #define PG8_LDB(dst, b, h) do { _Pragma("unroll") for (int n = 0; n < 2; ++n) _Pragma("unroll") for (int k = 0; k < 2; ++k) dst[n][k] = *(const PG8_LAS bf16x8*)(lds + PG8_SB(b, h) + boff + n * 2048 + k * 1024); } while (0)
; #define PG8_MMA(ai, bj, At, Bt) do { __builtin_amdgcn_s_setprio(1); _Pragma("unroll") for (int m = 0; m < 4; ++m) _Pragma("unroll") for (int n = 0; n < 2; ++n) _Pragma("unroll") for (int k = 0; k < 2; ++k) \
;         acc[ai][bj][m][n] = __builtin_amdgcn_mfma_f32_16x16x32_bf16(Bt[n][k], At[m][k], acc[ai][bj][m][n], 0, 0, 0); __builtin_amdgcn_s_setprio(0); } while (0)
; #define PG8_WAIT_V(n) asm volatile("s_waitcnt vmcnt(" #n ")" ::: "memory")
; #define PG8_WAIT_L(n) asm volatile("s_waitcnt lgkmcnt(" #n ")" ::: "memory")
; #define PG8_BAR __builtin_amdgcn_s_barrier()
; #define PG8_SCHED __builtin_amdgcn_sched_barrier(0)
; template <class Epi, class Sched, bool ALIGN_EPI = false, bool SP2 = false>
; __device__ __forceinline__ void gemm_phase(PG8_LAS unsigned char* lds, const Gemm g, const Sched& S, const Epi& E) {
;     ...
;             PG8_WAIT_V(8); PG8_WAIT_L(0); PG8_BAR; PG8_MMA(1, 0, At, B0); PG8_MMA(1, 1, At, B1); PG8_BAR; PG8_SCHED;
;             PG8_LDB(B0, 1, 0); PG8_LDB(B1, 1, 1); PG8_SCHED; PG8_LDA(At, 1, 0); PG8_STAGE(PG8_SA(0, 1), a2 + hstepA, voffA);
;             PG8_WAIT_V(8); PG8_WAIT_L(0); PG8_BAR; PG8_MMA(0, 0, At, B0); PG8_MMA(0, 1, At, B1); PG8_BAR; PG8_SCHED;
	s_setprio 1
	s_waitcnt lgkmcnt(0)
	v_mfma_f32_16x16x32_bf16 v[60:63], v[130:133], v[162:165], v[60:63]
	v_mfma_f32_16x16x32_bf16 v[56:59], v[138:141], v[162:165], v[56:59]
	v_mfma_f32_16x16x32_bf16 v[48:51], v[130:133], v[170:173], v[48:51]
	v_mfma_f32_16x16x32_bf16 v[40:43], v[138:141], v[170:173], v[40:43]
	v_mfma_f32_16x16x32_bf16 v[32:35], v[130:133], v[178:181], v[32:35]
	v_mfma_f32_16x16x32_bf16 v[24:27], v[138:141], v[178:181], v[24:27]
	v_mfma_f32_16x16x32_bf16 v[16:19], v[130:133], v[186:189], v[16:19]
	v_mfma_f32_16x16x32_bf16 v[8:11], v[138:141], v[186:189], v[8:11]
	v_mfma_f32_16x16x32_bf16 v[60:63], v[134:137], v[166:169], v[60:63]
	v_mfma_f32_16x16x32_bf16 v[56:59], v[142:145], v[166:169], v[56:59]
	v_mfma_f32_16x16x32_bf16 v[48:51], v[134:137], v[174:177], v[48:51]
	v_mfma_f32_16x16x32_bf16 v[40:43], v[142:145], v[174:177], v[40:43]
	v_mfma_f32_16x16x32_bf16 v[32:35], v[134:137], v[182:185], v[32:35]
	v_mfma_f32_16x16x32_bf16 v[24:27], v[142:145], v[182:185], v[24:27]
	v_mfma_f32_16x16x32_bf16 v[16:19], v[134:137], v[190:193], v[16:19]
	v_mfma_f32_16x16x32_bf16 v[8:11], v[142:145], v[190:193], v[8:11]
	s_setprio 0
	s_setprio 1
	v_mfma_f32_16x16x32_bf16 v[52:55], v[146:149], v[162:165], v[52:55]
	v_mfma_f32_16x16x32_bf16 v[44:47], v[154:157], v[162:165], v[44:47]
	v_mfma_f32_16x16x32_bf16 v[36:39], v[146:149], v[170:173], v[36:39]
	v_mfma_f32_16x16x32_bf16 v[28:31], v[154:157], v[170:173], v[28:31]
	v_mfma_f32_16x16x32_bf16 v[20:23], v[146:149], v[178:181], v[20:23]
	v_mfma_f32_16x16x32_bf16 v[12:15], v[154:157], v[178:181], v[12:15]
	v_mfma_f32_16x16x32_bf16 v[4:7], v[146:149], v[186:189], v[4:7]
	v_mfma_f32_16x16x32_bf16 v[0:3], v[154:157], v[186:189], v[0:3]
	v_mfma_f32_16x16x32_bf16 v[52:55], v[150:153], v[166:169], v[52:55]
	v_mfma_f32_16x16x32_bf16 v[44:47], v[158:161], v[166:169], v[44:47]
	v_mfma_f32_16x16x32_bf16 v[36:39], v[150:153], v[174:177], v[36:39]
	v_mfma_f32_16x16x32_bf16 v[28:31], v[158:161], v[174:177], v[28:31]
	v_mfma_f32_16x16x32_bf16 v[20:23], v[150:153], v[182:185], v[20:23]
	v_mfma_f32_16x16x32_bf16 v[12:15], v[158:161], v[182:185], v[12:15]
	v_mfma_f32_16x16x32_bf16 v[4:7], v[150:153], v[190:193], v[4:7]
	v_mfma_f32_16x16x32_bf16 v[0:3], v[158:161], v[190:193], v[0:3]
	s_setprio 0
	s_barrier
	v_add_u32_e32 v142, s28, v212
	v_add_u32_e32 v158, s29, v212
	ds_read_b128 v[130:133], v142
	ds_read_b128 v[134:137], v142 offset:1024
	ds_read_b128 v[138:141], v142 offset:2048
	ds_read_b128 v[142:145], v142 offset:3072
	ds_read_b128 v[146:149], v158
	ds_read_b128 v[150:153], v158 offset:1024
	ds_read_b128 v[154:157], v158 offset:2048
	ds_read_b128 v[158:161], v158 offset:3072
	s_add_u32 s26, s26, 0x60000
	s_addc_u32 s27, s27, 0
	s_mov_b32 m0, s34
	v_lshl_add_u64 v[218:219], s[26:27], 0, v[198:199]
	ds_read_b128 v[162:165], v213 offset:32768
	ds_read_b128 v[166:169], v213 offset:33792
	ds_read_b128 v[170:173], v213 offset:34816
	ds_read_b128 v[174:177], v213 offset:35840
	ds_read_b128 v[178:181], v213 offset:36864
	ds_read_b128 v[182:185], v213 offset:37888
	ds_read_b128 v[186:189], v213 offset:38912
	ds_read_b128 v[190:193], v213 offset:39936
	global_load_lds_dwordx4 v[218:219], off
	v_lshl_add_u64 v[218:219], s[26:27], 0, v[196:197]
	s_mov_b32 m0, s35
	s_nop 0
	global_load_lds_dwordx4 v[218:219], off
	s_waitcnt vmcnt(8)
	s_waitcnt lgkmcnt(0)
	s_barrier
	s_setprio 1
	s_waitcnt lgkmcnt(0)
	v_mfma_f32_16x16x32_bf16 v[126:129], v[130:133], v[162:165], v[126:129]
	v_mfma_f32_16x16x32_bf16 v[122:125], v[138:141], v[162:165], v[122:125]
	v_mfma_f32_16x16x32_bf16 v[114:117], v[130:133], v[170:173], v[114:117]
	v_mfma_f32_16x16x32_bf16 v[106:109], v[138:141], v[170:173], v[106:109]
	v_mfma_f32_16x16x32_bf16 v[98:101], v[130:133], v[178:181], v[98:101]
	v_mfma_f32_16x16x32_bf16 v[90:93], v[138:141], v[178:181], v[90:93]
	v_mfma_f32_16x16x32_bf16 v[82:85], v[130:133], v[186:189], v[82:85]
	v_mfma_f32_16x16x32_bf16 v[74:77], v[138:141], v[186:189], v[74:77]
	v_mfma_f32_16x16x32_bf16 v[126:129], v[134:137], v[166:169], v[126:129]
	v_mfma_f32_16x16x32_bf16 v[122:125], v[142:145], v[166:169], v[122:125]
	v_mfma_f32_16x16x32_bf16 v[114:117], v[134:137], v[174:177], v[114:117]
	v_mfma_f32_16x16x32_bf16 v[106:109], v[142:145], v[174:177], v[106:109]
	v_mfma_f32_16x16x32_bf16 v[98:101], v[134:137], v[182:185], v[98:101]
	v_mfma_f32_16x16x32_bf16 v[90:93], v[142:145], v[182:185], v[90:93]
	v_mfma_f32_16x16x32_bf16 v[82:85], v[134:137], v[190:193], v[82:85]
	v_mfma_f32_16x16x32_bf16 v[74:77], v[142:145], v[190:193], v[74:77]
	s_setprio 0
	s_setprio 1
	v_mfma_f32_16x16x32_bf16 v[118:121], v[146:149], v[162:165], v[118:121]
	v_mfma_f32_16x16x32_bf16 v[110:113], v[154:157], v[162:165], v[110:113]
	v_mfma_f32_16x16x32_bf16 v[102:105], v[146:149], v[170:173], v[102:105]
	v_mfma_f32_16x16x32_bf16 v[94:97], v[154:157], v[170:173], v[94:97]
	v_mfma_f32_16x16x32_bf16 v[86:89], v[146:149], v[178:181], v[86:89]
	v_mfma_f32_16x16x32_bf16 v[78:81], v[154:157], v[178:181], v[78:81]
	v_mfma_f32_16x16x32_bf16 v[70:73], v[146:149], v[186:189], v[70:73]
	v_mfma_f32_16x16x32_bf16 v[66:69], v[154:157], v[186:189], v[66:69]
	v_mfma_f32_16x16x32_bf16 v[118:121], v[150:153], v[166:169], v[118:121]
	v_mfma_f32_16x16x32_bf16 v[110:113], v[158:161], v[166:169], v[110:113]
	v_mfma_f32_16x16x32_bf16 v[102:105], v[150:153], v[174:177], v[102:105]
	v_mfma_f32_16x16x32_bf16 v[94:97], v[158:161], v[174:177], v[94:97]
	v_mfma_f32_16x16x32_bf16 v[86:89], v[150:153], v[182:185], v[86:89]
	v_mfma_f32_16x16x32_bf16 v[78:81], v[158:161], v[182:185], v[78:81]
	v_mfma_f32_16x16x32_bf16 v[70:73], v[150:153], v[190:193], v[70:73]
	v_mfma_f32_16x16x32_bf16 v[66:69], v[158:161], v[190:193], v[66:69]
	s_setprio 0
	s_barrier
; #define PG8_STAGE(bufoff, gbase, voff) do { _Pragma("unroll") for (int _i = 0; _i < 2; ++_i) \
;         __builtin_amdgcn_global_load_lds((const unsigned*)((const char*)(gbase) + (voff)[_i]), (PG8_LAS unsigned*)(lds + (bufoff) + ldsw + _i * 8192), 16, 0, 0); } while (0)
; #define PG8_LDA(dst, b, h) do { _Pragma("unroll") for (int m = 0; m < 4; ++m) _Pragma("unroll") for (int k = 0; k < 2; ++k) dst[m][k] = *(const PG8_LAS bf16x8*)(lds + PG8_SA(b, h) + aoff + m * 2048 + k * 1024); } while (0)
; #define PG8_MMA(ai, bj, At, Bt) do { __builtin_amdgcn_s_setprio(1); _Pragma("unroll") for (int m = 0; m < 4; ++m) _Pragma("unroll") for (int n = 0; n < 2; ++n) _Pragma("unroll") for (int k = 0; k < 2; ++k) \
;         acc[ai][bj][m][n] = __builtin_amdgcn_mfma_f32_16x16x32_bf16(Bt[n][k], At[m][k], acc[ai][bj][m][n], 0, 0, 0); __builtin_amdgcn_s_setprio(0); } while (0)
; #define PG8_WAIT_V(n) asm volatile("s_waitcnt vmcnt(" #n ")" ::: "memory")
; #define PG8_WAIT_L(n) asm volatile("s_waitcnt lgkmcnt(" #n ")" ::: "memory")
; #define PG8_BAR __builtin_amdgcn_s_barrier()
; #define PG8_SCHED __builtin_amdgcn_sched_barrier(0)
; template <class Epi, class Sched, bool ALIGN_EPI = false, bool SP2 = false>
; __device__ __forceinline__ void gemm_phase(PG8_LAS unsigned char* lds, const Gemm g, const Sched& S, const Epi& E) {
;     ...
;         for (int t = 0; t < nt; t += 2) {
;             const bool last = (t == nt - 2);
;     ...
;             PG8_LDA(At, 1, 1); PG8_STAGE(PG8_SB(1, 0), b3, voffB); PG8_STAGE(PG8_SB(1, 1), b3 + hstepB, voffB); PG8_STAGE(PG8_SA(1, 0), a3, voffA);
;             PG8_WAIT_V(8); PG8_WAIT_L(0); PG8_BAR; PG8_MMA(1, 0, At, B0); PG8_MMA(1, 1, At, B1); PG8_BAR; PG8_SCHED;
	s_add_i32 s26, s28, s67
	v_lshl_add_u64 v[208:209], v[208:209], 0, s[50:51]
	s_mov_b32 m0, s26
	ds_read_b128 v[162:165], v213 offset:49152
	ds_read_b128 v[166:169], v213 offset:50176
	ds_read_b128 v[170:173], v213 offset:51200
	ds_read_b128 v[174:177], v213 offset:52224
	ds_read_b128 v[178:181], v213 offset:53248
	ds_read_b128 v[182:185], v213 offset:54272
	ds_read_b128 v[186:189], v213 offset:55296
	ds_read_b128 v[190:193], v213 offset:56320
	global_load_lds_dwordx4 v[208:209], off
	s_add_i32 m0, s26, 0x2000
	s_add_u32 s26, vcc_lo, 0x20080
	v_lshl_add_u64 v[208:209], v[210:211], 0, s[50:51]
	s_addc_u32 s27, vcc_hi, 0
	s_add_i32 s72, s29, s67
	global_load_lds_dwordx4 v[208:209], off
	v_lshl_add_u64 v[208:209], s[26:27], 0, v[64:65]
	s_mov_b32 m0, s72
	s_nop 0
	global_load_lds_dwordx4 v[208:209], off
	v_lshl_add_u64 v[208:209], s[26:27], 0, v[194:195]
	s_add_i32 m0, s72, 0x2000
	s_nop 0
	global_load_lds_dwordx4 v[208:209], off
	v_lshl_add_u64 v[208:209], v[214:215], 0, s[50:51]
	s_mov_b32 m0, s79
	s_nop 0
	global_load_lds_dwordx4 v[208:209], off
	v_lshl_add_u64 v[208:209], v[216:217], 0, s[50:51]
	s_mov_b32 m0, s80
	s_nop 0
	global_load_lds_dwordx4 v[208:209], off
	s_waitcnt vmcnt(8)
	s_waitcnt lgkmcnt(0)
	s_barrier
	s_setprio 1
	s_waitcnt lgkmcnt(0)
	v_mfma_f32_16x16x32_bf16 v[60:63], v[130:133], v[162:165], v[60:63]
	v_mfma_f32_16x16x32_bf16 v[56:59], v[138:141], v[162:165], v[56:59]
	v_mfma_f32_16x16x32_bf16 v[48:51], v[130:133], v[170:173], v[48:51]
	v_mfma_f32_16x16x32_bf16 v[40:43], v[138:141], v[170:173], v[40:43]
	v_mfma_f32_16x16x32_bf16 v[32:35], v[130:133], v[178:181], v[32:35]
	v_mfma_f32_16x16x32_bf16 v[24:27], v[138:141], v[178:181], v[24:27]
	v_mfma_f32_16x16x32_bf16 v[16:19], v[130:133], v[186:189], v[16:19]
	v_mfma_f32_16x16x32_bf16 v[8:11], v[138:141], v[186:189], v[8:11]
	v_mfma_f32_16x16x32_bf16 v[60:63], v[134:137], v[166:169], v[60:63]
	v_mfma_f32_16x16x32_bf16 v[56:59], v[142:145], v[166:169], v[56:59]
	v_mfma_f32_16x16x32_bf16 v[48:51], v[134:137], v[174:177], v[48:51]
	v_mfma_f32_16x16x32_bf16 v[40:43], v[142:145], v[174:177], v[40:43]
	v_mfma_f32_16x16x32_bf16 v[32:35], v[134:137], v[182:185], v[32:35]
	v_mfma_f32_16x16x32_bf16 v[24:27], v[142:145], v[182:185], v[24:27]
	v_mfma_f32_16x16x32_bf16 v[16:19], v[134:137], v[190:193], v[16:19]
	v_mfma_f32_16x16x32_bf16 v[8:11], v[142:145], v[190:193], v[8:11]
	s_setprio 0
	s_setprio 1
	v_mfma_f32_16x16x32_bf16 v[52:55], v[146:149], v[162:165], v[52:55]
	v_mfma_f32_16x16x32_bf16 v[44:47], v[154:157], v[162:165], v[44:47]
	v_mfma_f32_16x16x32_bf16 v[36:39], v[146:149], v[170:173], v[36:39]
	v_mfma_f32_16x16x32_bf16 v[28:31], v[154:157], v[170:173], v[28:31]
	v_mfma_f32_16x16x32_bf16 v[20:23], v[146:149], v[178:181], v[20:23]
	v_mfma_f32_16x16x32_bf16 v[12:15], v[154:157], v[178:181], v[12:15]
	v_mfma_f32_16x16x32_bf16 v[4:7], v[146:149], v[186:189], v[4:7]
	v_mfma_f32_16x16x32_bf16 v[0:3], v[154:157], v[186:189], v[0:3]
	v_mfma_f32_16x16x32_bf16 v[52:55], v[150:153], v[166:169], v[52:55]
	v_mfma_f32_16x16x32_bf16 v[44:47], v[158:161], v[166:169], v[44:47]
	v_mfma_f32_16x16x32_bf16 v[36:39], v[150:153], v[174:177], v[36:39]
	v_mfma_f32_16x16x32_bf16 v[28:31], v[158:161], v[174:177], v[28:31]
	v_mfma_f32_16x16x32_bf16 v[20:23], v[150:153], v[182:185], v[20:23]
	v_mfma_f32_16x16x32_bf16 v[12:15], v[158:161], v[182:185], v[12:15]
	v_mfma_f32_16x16x32_bf16 v[4:7], v[150:153], v[190:193], v[4:7]
	v_mfma_f32_16x16x32_bf16 v[0:3], v[158:161], v[190:193], v[0:3]
	s_setprio 0
	s_add_i32 s71, s71, 2
	s_add_u32 s0, s0, 0x100
	s_addc_u32 s1, s1, 0
	s_add_u32 s55, s55, 0x100
	s_addc_u32 s70, s70, 0
	s_cmp_gt_u32 s71, 5
	s_barrier
	s_cbranch_scc0 .LBB0_488
	s_and_b64 vcc, exec, s[14:15]
	s_cbranch_vccz .LBB0_491
	s_barrier

; #define PG8_STAGE(bufoff, gbase, voff) do { _Pragma("unroll") for (int _i = 0; _i < 2; ++_i) \
;         __builtin_amdgcn_global_load_lds((const unsigned*)((const char*)(gbase) + (voff)[_i]), (PG8_LAS unsigned*)(lds + (bufoff) + ldsw + _i * 8192), 16, 0, 0); } while (0)
; #define PG8_LDA(dst, b, h) do { _Pragma("unroll") for (int m = 0; m < 4; ++m) _Pragma("unroll") for (int k = 0; k < 2; ++k) dst[m][k] = *(const PG8_LAS bf16x8*)(lds + PG8_SA(b, h) + aoff + m * 2048 + k * 1024); } while (0)
; #define PG8_LDB(dst, b, h) do { _Pragma("unroll") for (int n = 0; n < 2; ++n) _Pragma("unroll") for (int k = 0; k < 2; ++k) dst[n][k] = *(const PG8_LAS bf16x8*)(lds + PG8_SB(b, h) + boff + n * 2048 + k * 1024); } while (0)
; #define PG8_MMA(ai, bj, At, Bt) do { __builtin_amdgcn_s_setprio(1); _Pragma("unroll") for (int m = 0; m < 4; ++m) _Pragma("unroll") for (int n = 0; n < 2; ++n) _Pragma("unroll") for (int k = 0; k < 2; ++k) \
;         acc[ai][bj][m][n] = __builtin_amdgcn_mfma_f32_16x16x32_bf16(Bt[n][k], At[m][k], acc[ai][bj][m][n], 0, 0, 0); __builtin_amdgcn_s_setprio(0); } while (0)
; #define PG8_WAIT_V(n) asm volatile("s_waitcnt vmcnt(" #n ")" ::: "memory")
; #define PG8_BAR __builtin_amdgcn_s_barrier()
; template <class Epi, class Sched, bool ALIGN_EPI = false, bool SP2 = false>
; __device__ __forceinline__ void gemm_phase(PG8_LAS unsigned char* lds, const Gemm g, const Sched& S, const Epi& E) {
;     ...
;         for (int t = 0; t < nt; t += 2) {
;             const bool last = (t == nt - 2);
;             const char* a1 = cA + (size_t)(t + 1) * kstep;
;             const char* a2 = last ? nA : cA + (size_t)(t + 2) * kstep; const char* b2 = last ? nB : cB + (size_t)(t + 2) * kstep;
;             const char* a3 = a2 + kstep; const char* b3 = b2 + kstep;
;             if (last && has_next) S.a_ready(nxt);
;             if constexpr (SP2) {
;             PG8_LDB(B0, 0, 0); PG8_LDB(B1, 0, 1); PG8_SCHED; PG8_LDA(At, 0, 0); PG8_STAGE(PG8_SA(1, 1), a1 + hstepA, voffA);
;             PG8_WAIT_V(8); PG8_WAIT_L(0); PG8_BAR; PG8_MMA(0, 0, At, B0); PG8_MMA(0, 1, At, B1); PG8_BAR; PG8_SCHED;
;             PG8_LDA(At, 0, 1); PG8_STAGE(PG8_SB(0, 0), b2, voffB); PG8_STAGE(PG8_SB(0, 1), b2 + hstepB, voffB); PG8_STAGE(PG8_SA(0, 0), a2, voffA);
;             PG8_WAIT_V(8); PG8_WAIT_L(0); PG8_BAR; PG8_MMA(1, 0, At, B0); PG8_MMA(1, 1, At, B1); PG8_BAR; PG8_SCHED;
.LBB0_532:
	v_add_u32_e32 v156, s21, v142
	v_add_u32_e32 v172, s91, v142
	s_add_u32 s44, s24, 0x100
	ds_read_b128 v[144:147], v156
	ds_read_b128 v[148:151], v156 offset:1024
	ds_read_b128 v[152:155], v156 offset:2048
	ds_read_b128 v[156:159], v156 offset:3072
	ds_read_b128 v[160:163], v172
	ds_read_b128 v[164:167], v172 offset:1024
	ds_read_b128 v[168:171], v172 offset:2048
	ds_read_b128 v[172:175], v172 offset:3072
	s_addc_u32 s45, s25, 0
	s_add_u32 s26, s46, s24
	s_addc_u32 s27, s54, s25
	s_cmp_eq_u32 s55, 12
	s_cselect_b32 s71, 0, s44
	s_cselect_b32 s70, 0, s45
	s_cselect_b32 s52, s14, s26
	s_cselect_b32 s53, s15, s27
	s_add_u32 s26, s0, s71
	s_addc_u32 s27, s1, s70
	v_lshl_add_u64 v[204:205], v[138:139], 0, s[24:25]
	s_add_i32 m0, s31, 0xc000
	ds_read_b128 v[176:179], v143
	ds_read_b128 v[180:183], v143 offset:1024
	ds_read_b128 v[184:187], v143 offset:2048
	ds_read_b128 v[188:191], v143 offset:3072
	ds_read_b128 v[192:195], v143 offset:4096
	ds_read_b128 v[196:199], v143 offset:5120
	ds_read_b128 v[200:203], v143 offset:6144
	ds_read_b128 v[208:211], v143 offset:7168
	global_load_lds_dwordx4 v[204:205], off
	v_lshl_add_u64 v[204:205], v[140:141], 0, s[24:25]
	s_add_i32 m0, s31, 0xe000
	s_nop 0
	global_load_lds_dwordx4 v[204:205], off
	s_waitcnt vmcnt(8)
	s_waitcnt lgkmcnt(0)
	s_barrier
	s_setprio 1
	s_waitcnt lgkmcnt(0)
	v_mfma_f32_16x16x32_bf16 v[126:129], v[144:147], v[176:179], v[126:129]
	v_mfma_f32_16x16x32_bf16 v[122:125], v[152:155], v[176:179], v[122:125]
	v_mfma_f32_16x16x32_bf16 v[118:121], v[144:147], v[184:187], v[118:121]
	v_mfma_f32_16x16x32_bf16 v[114:117], v[152:155], v[184:187], v[114:117]
	v_mfma_f32_16x16x32_bf16 v[102:105], v[144:147], v[192:195], v[102:105]
	v_mfma_f32_16x16x32_bf16 v[98:101], v[152:155], v[192:195], v[98:101]
	v_mfma_f32_16x16x32_bf16 v[86:89], v[144:147], v[200:203], v[86:89]
	v_mfma_f32_16x16x32_bf16 v[82:85], v[152:155], v[200:203], v[82:85]
	v_mfma_f32_16x16x32_bf16 v[126:129], v[148:151], v[180:183], v[126:129]
	v_mfma_f32_16x16x32_bf16 v[122:125], v[156:159], v[180:183], v[122:125]
	v_mfma_f32_16x16x32_bf16 v[118:121], v[148:151], v[188:191], v[118:121]
	v_mfma_f32_16x16x32_bf16 v[114:117], v[156:159], v[188:191], v[114:117]
	v_mfma_f32_16x16x32_bf16 v[102:105], v[148:151], v[196:199], v[102:105]
	v_mfma_f32_16x16x32_bf16 v[98:101], v[156:159], v[196:199], v[98:101]
	v_mfma_f32_16x16x32_bf16 v[86:89], v[148:151], v[208:211], v[86:89]
	v_mfma_f32_16x16x32_bf16 v[82:85], v[156:159], v[208:211], v[82:85]
	s_setprio 0
	s_setprio 1
	v_mfma_f32_16x16x32_bf16 v[110:113], v[160:163], v[176:179], v[110:113]
	v_mfma_f32_16x16x32_bf16 v[106:109], v[168:171], v[176:179], v[106:109]
	v_mfma_f32_16x16x32_bf16 v[94:97], v[160:163], v[184:187], v[94:97]
	v_mfma_f32_16x16x32_bf16 v[90:93], v[168:171], v[184:187], v[90:93]
	v_mfma_f32_16x16x32_bf16 v[78:81], v[160:163], v[192:195], v[78:81]
	v_mfma_f32_16x16x32_bf16 v[74:77], v[168:171], v[192:195], v[74:77]
	v_mfma_f32_16x16x32_bf16 v[70:73], v[160:163], v[200:203], v[70:73]
	v_mfma_f32_16x16x32_bf16 v[66:69], v[168:171], v[200:203], v[66:69]
	v_mfma_f32_16x16x32_bf16 v[110:113], v[164:167], v[180:183], v[110:113]
	v_mfma_f32_16x16x32_bf16 v[106:109], v[172:175], v[180:183], v[106:109]
	v_mfma_f32_16x16x32_bf16 v[94:97], v[164:167], v[188:191], v[94:97]
	v_mfma_f32_16x16x32_bf16 v[90:93], v[172:175], v[188:191], v[90:93]
	v_mfma_f32_16x16x32_bf16 v[78:81], v[164:167], v[196:199], v[78:81]
	v_mfma_f32_16x16x32_bf16 v[74:77], v[172:175], v[196:199], v[74:77]
	v_mfma_f32_16x16x32_bf16 v[70:73], v[164:167], v[208:211], v[70:73]
	v_mfma_f32_16x16x32_bf16 v[66:69], v[172:175], v[208:211], v[66:69]
	s_setprio 0
	s_barrier
	s_add_i32 s24, s21, s30
	v_lshl_add_u64 v[204:205], s[52:53], 0, v[134:135]
	s_mov_b32 m0, s24
	ds_read_b128 v[176:179], v143 offset:16384
	ds_read_b128 v[180:183], v143 offset:17408
	ds_read_b128 v[184:187], v143 offset:18432
	ds_read_b128 v[188:191], v143 offset:19456
	ds_read_b128 v[192:195], v143 offset:20480
	ds_read_b128 v[196:199], v143 offset:21504
	ds_read_b128 v[200:203], v143 offset:22528
	ds_read_b128 v[208:211], v143 offset:23552
	global_load_lds_dwordx4 v[204:205], off
	s_add_i32 m0, s24, 0x2000
	s_add_u32 s24, s52, 0x40000
	v_lshl_add_u64 v[212:213], s[52:53], 0, v[130:131]
	s_addc_u32 s25, s53, 0
	s_add_i32 s70, s91, s30
	global_load_lds_dwordx4 v[212:213], off
	v_lshl_add_u64 v[214:215], s[24:25], 0, v[134:135]
	s_mov_b32 m0, s70
	v_lshl_add_u64 v[216:217], s[26:27], 0, v[132:133]
	global_load_lds_dwordx4 v[214:215], off
	v_lshl_add_u64 v[214:215], s[24:25], 0, v[130:131]
	s_add_i32 m0, s70, 0x2000
	s_nop 0
	global_load_lds_dwordx4 v[214:215], off
	v_lshl_add_u64 v[214:215], s[26:27], 0, v[64:65]
	s_mov_b32 m0, s31
	s_nop 0
	global_load_lds_dwordx4 v[214:215], off
	s_mov_b32 m0, s34
	s_nop 0
	global_load_lds_dwordx4 v[216:217], off
	s_waitcnt vmcnt(8)
	s_waitcnt lgkmcnt(0)
	s_barrier
; #define PG8_STAGE(bufoff, gbase, voff) do { _Pragma("unroll") for (int _i = 0; _i < 2; ++_i) \
;         __builtin_amdgcn_global_load_lds((const unsigned*)((const char*)(gbase) + (voff)[_i]), (PG8_LAS unsigned*)(lds + (bufoff) + ldsw + _i * 8192), 16, 0, 0); } while (0)
; #define PG8_LDA(dst, b, h) do { _Pragma("unroll") for (int m = 0; m < 4; ++m) _Pragma("unroll") for (int k = 0; k < 2; ++k) dst[m][k] = *(const PG8_LAS bf16x8*)(lds + PG8_SA(b, h) + aoff + m * 2048 + k * 1024); } while (0)
; #define PG8_LDB(dst, b, h) do { _Pragma("unroll") for (int n = 0; n < 2; ++n) _Pragma("unroll") for (int k = 0; k < 2; ++k) dst[n][k] = *(const PG8_LAS bf16x8*)(lds + PG8_SB(b, h) + boff + n * 2048 + k * 1024); } while (0)
; #define PG8_MMA(ai, bj, At, Bt) do { __builtin_amdgcn_s_setprio(1); _Pragma("unroll") for (int m = 0; m < 4; ++m) _Pragma("unroll") for (int n = 0; n < 2; ++n) _Pragma("unroll") for (int k = 0; k < 2; ++k) \
;         acc[ai][bj][m][n] = __builtin_amdgcn_mfma_f32_16x16x32_bf16(Bt[n][k], At[m][k], acc[ai][bj][m][n], 0, 0, 0); __builtin_amdgcn_s_setprio(0); } while (0)
; #define PG8_WAIT_V(n) asm volatile("s_waitcnt vmcnt(" #n ")" ::: "memory")
; #define PG8_WAIT_L(n) asm volatile("s_waitcnt lgkmcnt(" #n ")" ::: "memory")
; #define PG8_BAR __builtin_amdgcn_s_barrier()
; #define PG8_SCHED __builtin_amdgcn_sched_barrier(0)
; template <class Epi, class Sched, bool ALIGN_EPI = false, bool SP2 = false>
; __device__ __forceinline__ void gemm_phase(PG8_LAS unsigned char* lds, const Gemm g, const Sched& S, const Epi& E) {
;     ...
;             PG8_WAIT_V(8); PG8_WAIT_L(0); PG8_BAR; PG8_MMA(1, 0, At, B0); PG8_MMA(1, 1, At, B1); PG8_BAR; PG8_SCHED;
;             PG8_LDB(B0, 1, 0); PG8_LDB(B1, 1, 1); PG8_SCHED; PG8_LDA(At, 1, 0); PG8_STAGE(PG8_SA(0, 1), a2 + hstepA, voffA);
;             PG8_WAIT_V(8); PG8_WAIT_L(0); PG8_BAR; PG8_MMA(0, 0, At, B0); PG8_MMA(0, 1, At, B1); PG8_BAR; PG8_SCHED;
	s_setprio 1
	s_waitcnt lgkmcnt(0)
	v_mfma_f32_16x16x32_bf16 v[60:63], v[144:147], v[176:179], v[60:63]
	v_mfma_f32_16x16x32_bf16 v[56:59], v[152:155], v[176:179], v[56:59]
	v_mfma_f32_16x16x32_bf16 v[52:55], v[144:147], v[184:187], v[52:55]
	v_mfma_f32_16x16x32_bf16 v[48:51], v[152:155], v[184:187], v[48:51]
	v_mfma_f32_16x16x32_bf16 v[36:39], v[144:147], v[192:195], v[36:39]
	v_mfma_f32_16x16x32_bf16 v[32:35], v[152:155], v[192:195], v[32:35]
	v_mfma_f32_16x16x32_bf16 v[20:23], v[144:147], v[200:203], v[20:23]
	v_mfma_f32_16x16x32_bf16 v[16:19], v[152:155], v[200:203], v[16:19]
	v_mfma_f32_16x16x32_bf16 v[60:63], v[148:151], v[180:183], v[60:63]
	v_mfma_f32_16x16x32_bf16 v[56:59], v[156:159], v[180:183], v[56:59]
	v_mfma_f32_16x16x32_bf16 v[52:55], v[148:151], v[188:191], v[52:55]
	v_mfma_f32_16x16x32_bf16 v[48:51], v[156:159], v[188:191], v[48:51]
	v_mfma_f32_16x16x32_bf16 v[36:39], v[148:151], v[196:199], v[36:39]
	v_mfma_f32_16x16x32_bf16 v[32:35], v[156:159], v[196:199], v[32:35]
	v_mfma_f32_16x16x32_bf16 v[20:23], v[148:151], v[208:211], v[20:23]
	v_mfma_f32_16x16x32_bf16 v[16:19], v[156:159], v[208:211], v[16:19]
	s_setprio 0
	s_setprio 1
	v_mfma_f32_16x16x32_bf16 v[44:47], v[160:163], v[176:179], v[44:47]
	v_mfma_f32_16x16x32_bf16 v[40:43], v[168:171], v[176:179], v[40:43]
	v_mfma_f32_16x16x32_bf16 v[28:31], v[160:163], v[184:187], v[28:31]
	v_mfma_f32_16x16x32_bf16 v[24:27], v[168:171], v[184:187], v[24:27]
	v_mfma_f32_16x16x32_bf16 v[12:15], v[160:163], v[192:195], v[12:15]
	v_mfma_f32_16x16x32_bf16 v[8:11], v[168:171], v[192:195], v[8:11]
	v_mfma_f32_16x16x32_bf16 v[4:7], v[160:163], v[200:203], v[4:7]
	v_mfma_f32_16x16x32_bf16 v[0:3], v[168:171], v[200:203], v[0:3]
	v_mfma_f32_16x16x32_bf16 v[44:47], v[164:167], v[180:183], v[44:47]
	v_mfma_f32_16x16x32_bf16 v[40:43], v[172:175], v[180:183], v[40:43]
	v_mfma_f32_16x16x32_bf16 v[28:31], v[164:167], v[188:191], v[28:31]
	v_mfma_f32_16x16x32_bf16 v[24:27], v[172:175], v[188:191], v[24:27]
	v_mfma_f32_16x16x32_bf16 v[12:15], v[164:167], v[196:199], v[12:15]
	v_mfma_f32_16x16x32_bf16 v[8:11], v[172:175], v[196:199], v[8:11]
	v_mfma_f32_16x16x32_bf16 v[4:7], v[164:167], v[208:211], v[4:7]
	v_mfma_f32_16x16x32_bf16 v[0:3], v[172:175], v[208:211], v[0:3]
	s_setprio 0
	s_barrier
	v_add_u32_e32 v156, s28, v142
	v_add_u32_e32 v172, s29, v142
	ds_read_b128 v[144:147], v156
	ds_read_b128 v[148:151], v156 offset:1024
	ds_read_b128 v[152:155], v156 offset:2048
	ds_read_b128 v[156:159], v156 offset:3072
	ds_read_b128 v[160:163], v172
	ds_read_b128 v[164:167], v172 offset:1024
	ds_read_b128 v[168:171], v172 offset:2048
	ds_read_b128 v[172:175], v172 offset:3072
	s_add_u32 s24, s26, 0x40000
	s_addc_u32 s25, s27, 0
	s_mov_b32 m0, s35
	v_lshl_add_u64 v[218:219], s[24:25], 0, v[64:65]
	ds_read_b128 v[176:179], v143 offset:32768
	ds_read_b128 v[180:183], v143 offset:33792
	ds_read_b128 v[184:187], v143 offset:34816
	ds_read_b128 v[188:191], v143 offset:35840
	ds_read_b128 v[192:195], v143 offset:36864
	ds_read_b128 v[196:199], v143 offset:37888
	ds_read_b128 v[200:203], v143 offset:38912
	ds_read_b128 v[208:211], v143 offset:39936
	global_load_lds_dwordx4 v[218:219], off
	v_lshl_add_u64 v[218:219], s[24:25], 0, v[132:133]
	s_mov_b32 m0, s59
	s_nop 0
	global_load_lds_dwordx4 v[218:219], off
	s_waitcnt vmcnt(8)
	s_waitcnt lgkmcnt(0)
	s_barrier
	s_setprio 1
	s_waitcnt lgkmcnt(0)
	v_mfma_f32_16x16x32_bf16 v[126:129], v[144:147], v[176:179], v[126:129]
	v_mfma_f32_16x16x32_bf16 v[122:125], v[152:155], v[176:179], v[122:125]
	v_mfma_f32_16x16x32_bf16 v[118:121], v[144:147], v[184:187], v[118:121]
	v_mfma_f32_16x16x32_bf16 v[114:117], v[152:155], v[184:187], v[114:117]
	v_mfma_f32_16x16x32_bf16 v[102:105], v[144:147], v[192:195], v[102:105]
	v_mfma_f32_16x16x32_bf16 v[98:101], v[152:155], v[192:195], v[98:101]
	v_mfma_f32_16x16x32_bf16 v[86:89], v[144:147], v[200:203], v[86:89]
	v_mfma_f32_16x16x32_bf16 v[82:85], v[152:155], v[200:203], v[82:85]
	v_mfma_f32_16x16x32_bf16 v[126:129], v[148:151], v[180:183], v[126:129]
	v_mfma_f32_16x16x32_bf16 v[122:125], v[156:159], v[180:183], v[122:125]
	v_mfma_f32_16x16x32_bf16 v[118:121], v[148:151], v[188:191], v[118:121]
	v_mfma_f32_16x16x32_bf16 v[114:117], v[156:159], v[188:191], v[114:117]
	v_mfma_f32_16x16x32_bf16 v[102:105], v[148:151], v[196:199], v[102:105]
	v_mfma_f32_16x16x32_bf16 v[98:101], v[156:159], v[196:199], v[98:101]
	v_mfma_f32_16x16x32_bf16 v[86:89], v[148:151], v[208:211], v[86:89]
	v_mfma_f32_16x16x32_bf16 v[82:85], v[156:159], v[208:211], v[82:85]
	s_setprio 0
	s_setprio 1
	v_mfma_f32_16x16x32_bf16 v[110:113], v[160:163], v[176:179], v[110:113]
	v_mfma_f32_16x16x32_bf16 v[106:109], v[168:171], v[176:179], v[106:109]
	v_mfma_f32_16x16x32_bf16 v[94:97], v[160:163], v[184:187], v[94:97]
	v_mfma_f32_16x16x32_bf16 v[90:93], v[168:171], v[184:187], v[90:93]
	v_mfma_f32_16x16x32_bf16 v[78:81], v[160:163], v[192:195], v[78:81]
	v_mfma_f32_16x16x32_bf16 v[74:77], v[168:171], v[192:195], v[74:77]
	v_mfma_f32_16x16x32_bf16 v[70:73], v[160:163], v[200:203], v[70:73]
	v_mfma_f32_16x16x32_bf16 v[66:69], v[168:171], v[200:203], v[66:69]
	v_mfma_f32_16x16x32_bf16 v[110:113], v[164:167], v[180:183], v[110:113]
	v_mfma_f32_16x16x32_bf16 v[106:109], v[172:175], v[180:183], v[106:109]
	v_mfma_f32_16x16x32_bf16 v[94:97], v[164:167], v[188:191], v[94:97]
	v_mfma_f32_16x16x32_bf16 v[90:93], v[172:175], v[188:191], v[90:93]
	v_mfma_f32_16x16x32_bf16 v[78:81], v[164:167], v[196:199], v[78:81]
	v_mfma_f32_16x16x32_bf16 v[74:77], v[172:175], v[196:199], v[74:77]
	v_mfma_f32_16x16x32_bf16 v[70:73], v[164:167], v[208:211], v[70:73]
	v_mfma_f32_16x16x32_bf16 v[66:69], v[172:175], v[208:211], v[66:69]
	s_setprio 0
	s_barrier
; #define PG8_STAGE(bufoff, gbase, voff) do { _Pragma("unroll") for (int _i = 0; _i < 2; ++_i) \
;         __builtin_amdgcn_global_load_lds((const unsigned*)((const char*)(gbase) + (voff)[_i]), (PG8_LAS unsigned*)(lds + (bufoff) + ldsw + _i * 8192), 16, 0, 0); } while (0)
; #define PG8_LDA(dst, b, h) do { _Pragma("unroll") for (int m = 0; m < 4; ++m) _Pragma("unroll") for (int k = 0; k < 2; ++k) dst[m][k] = *(const PG8_LAS bf16x8*)(lds + PG8_SA(b, h) + aoff + m * 2048 + k * 1024); } while (0)
; #define PG8_MMA(ai, bj, At, Bt) do { __builtin_amdgcn_s_setprio(1); _Pragma("unroll") for (int m = 0; m < 4; ++m) _Pragma("unroll") for (int n = 0; n < 2; ++n) _Pragma("unroll") for (int k = 0; k < 2; ++k) \
;         acc[ai][bj][m][n] = __builtin_amdgcn_mfma_f32_16x16x32_bf16(Bt[n][k], At[m][k], acc[ai][bj][m][n], 0, 0, 0); __builtin_amdgcn_s_setprio(0); } while (0)
; #define PG8_WAIT_V(n) asm volatile("s_waitcnt vmcnt(" #n ")" ::: "memory")
; #define PG8_WAIT_L(n) asm volatile("s_waitcnt lgkmcnt(" #n ")" ::: "memory")
; #define PG8_BAR __builtin_amdgcn_s_barrier()
; #define PG8_SCHED __builtin_amdgcn_sched_barrier(0)
; template <class Epi, class Sched, bool ALIGN_EPI = false, bool SP2 = false>
; __device__ __forceinline__ void gemm_phase(PG8_LAS unsigned char* lds, const Gemm g, const Sched& S, const Epi& E) {
;     ...
;         for (int t = 0; t < nt; t += 2) {
;             const bool last = (t == nt - 2);
;     ...
;             PG8_LDA(At, 1, 1); PG8_STAGE(PG8_SB(1, 0), b3, voffB); PG8_STAGE(PG8_SB(1, 1), b3 + hstepB, voffB); PG8_STAGE(PG8_SA(1, 0), a3, voffA);
;             PG8_WAIT_V(8); PG8_WAIT_L(0); PG8_BAR; PG8_MMA(1, 0, At, B0); PG8_MMA(1, 1, At, B1); PG8_BAR; PG8_SCHED;
	s_add_i32 s24, s28, s30
	v_lshl_add_u64 v[204:205], v[204:205], 0, s[50:51]
	s_mov_b32 m0, s24
	ds_read_b128 v[176:179], v143 offset:49152
	ds_read_b128 v[180:183], v143 offset:50176
	ds_read_b128 v[184:187], v143 offset:51200
	ds_read_b128 v[188:191], v143 offset:52224
	ds_read_b128 v[192:195], v143 offset:53248
	ds_read_b128 v[196:199], v143 offset:54272
	ds_read_b128 v[200:203], v143 offset:55296
	ds_read_b128 v[208:211], v143 offset:56320
	global_load_lds_dwordx4 v[204:205], off
	s_add_i32 m0, s24, 0x2000
	s_add_u32 s24, s52, 0x40080
	v_lshl_add_u64 v[204:205], v[212:213], 0, s[50:51]
	s_addc_u32 s25, s53, 0
	s_add_i32 s26, s29, s30
	global_load_lds_dwordx4 v[204:205], off
	v_lshl_add_u64 v[204:205], s[24:25], 0, v[134:135]
	s_mov_b32 m0, s26
	s_nop 0
	global_load_lds_dwordx4 v[204:205], off
	v_lshl_add_u64 v[204:205], s[24:25], 0, v[130:131]
	s_add_i32 m0, s26, 0x2000
	s_nop 0
	global_load_lds_dwordx4 v[204:205], off
	v_lshl_add_u64 v[204:205], v[214:215], 0, s[50:51]
	s_mov_b32 m0, s62
	s_nop 0
	global_load_lds_dwordx4 v[204:205], off
	v_lshl_add_u64 v[204:205], v[216:217], 0, s[50:51]
	s_mov_b32 m0, s67
	s_nop 0
	global_load_lds_dwordx4 v[204:205], off
	s_waitcnt vmcnt(8)
	s_waitcnt lgkmcnt(0)
	s_barrier
	s_setprio 1
	s_waitcnt lgkmcnt(0)
	v_mfma_f32_16x16x32_bf16 v[60:63], v[144:147], v[176:179], v[60:63]
	v_mfma_f32_16x16x32_bf16 v[56:59], v[152:155], v[176:179], v[56:59]
	v_mfma_f32_16x16x32_bf16 v[52:55], v[144:147], v[184:187], v[52:55]
	v_mfma_f32_16x16x32_bf16 v[48:51], v[152:155], v[184:187], v[48:51]
	v_mfma_f32_16x16x32_bf16 v[36:39], v[144:147], v[192:195], v[36:39]
	v_mfma_f32_16x16x32_bf16 v[32:35], v[152:155], v[192:195], v[32:35]
	v_mfma_f32_16x16x32_bf16 v[20:23], v[144:147], v[200:203], v[20:23]
	v_mfma_f32_16x16x32_bf16 v[16:19], v[152:155], v[200:203], v[16:19]
	v_mfma_f32_16x16x32_bf16 v[60:63], v[148:151], v[180:183], v[60:63]
	v_mfma_f32_16x16x32_bf16 v[56:59], v[156:159], v[180:183], v[56:59]
	v_mfma_f32_16x16x32_bf16 v[52:55], v[148:151], v[188:191], v[52:55]
	v_mfma_f32_16x16x32_bf16 v[48:51], v[156:159], v[188:191], v[48:51]
	v_mfma_f32_16x16x32_bf16 v[36:39], v[148:151], v[196:199], v[36:39]
	v_mfma_f32_16x16x32_bf16 v[32:35], v[156:159], v[196:199], v[32:35]
	v_mfma_f32_16x16x32_bf16 v[20:23], v[148:151], v[208:211], v[20:23]
	v_mfma_f32_16x16x32_bf16 v[16:19], v[156:159], v[208:211], v[16:19]
	s_setprio 0
	s_setprio 1
	v_mfma_f32_16x16x32_bf16 v[44:47], v[160:163], v[176:179], v[44:47]
	v_mfma_f32_16x16x32_bf16 v[40:43], v[168:171], v[176:179], v[40:43]
	v_mfma_f32_16x16x32_bf16 v[28:31], v[160:163], v[184:187], v[28:31]
	v_mfma_f32_16x16x32_bf16 v[24:27], v[168:171], v[184:187], v[24:27]
	v_mfma_f32_16x16x32_bf16 v[12:15], v[160:163], v[192:195], v[12:15]
	v_mfma_f32_16x16x32_bf16 v[8:11], v[168:171], v[192:195], v[8:11]
	v_mfma_f32_16x16x32_bf16 v[4:7], v[160:163], v[200:203], v[4:7]
	v_mfma_f32_16x16x32_bf16 v[0:3], v[168:171], v[200:203], v[0:3]
	v_mfma_f32_16x16x32_bf16 v[44:47], v[164:167], v[180:183], v[44:47]
	v_mfma_f32_16x16x32_bf16 v[40:43], v[172:175], v[180:183], v[40:43]
	v_mfma_f32_16x16x32_bf16 v[28:31], v[164:167], v[188:191], v[28:31]
	v_mfma_f32_16x16x32_bf16 v[24:27], v[172:175], v[188:191], v[24:27]
	v_mfma_f32_16x16x32_bf16 v[12:15], v[164:167], v[196:199], v[12:15]
	v_mfma_f32_16x16x32_bf16 v[8:11], v[172:175], v[196:199], v[8:11]
	v_mfma_f32_16x16x32_bf16 v[4:7], v[164:167], v[208:211], v[4:7]
	v_mfma_f32_16x16x32_bf16 v[0:3], v[172:175], v[208:211], v[0:3]
	s_setprio 0
	s_add_i32 s55, s55, 2
	s_cmp_gt_u32 s55, 13
	s_mov_b64 s[24:25], s[44:45]
	s_barrier
	s_cbranch_scc0 .LBB0_532
	s_and_b64 vcc, exec, s[12:13]
	s_cbranch_vccz .LBB0_535
	s_barrier

; #define PG8_STAGE(bufoff, gbase, voff) do { _Pragma("unroll") for (int _i = 0; _i < 2; ++_i) \
;         __builtin_amdgcn_global_load_lds((const unsigned*)((const char*)(gbase) + (voff)[_i]), (PG8_LAS unsigned*)(lds + (bufoff) + ldsw + _i * 8192), 16, 0, 0); } while (0)
; #define PG8_LDA(dst, b, h) do { _Pragma("unroll") for (int m = 0; m < 4; ++m) _Pragma("unroll") for (int k = 0; k < 2; ++k) dst[m][k] = *(const PG8_LAS bf16x8*)(lds + PG8_SA(b, h) + aoff + m * 2048 + k * 1024); } while (0)
; #define PG8_LDB(dst, b, h) do { _Pragma("unroll") for (int n = 0; n < 2; ++n) _Pragma("unroll") for (int k = 0; k < 2; ++k) dst[n][k] = *(const PG8_LAS bf16x8*)(lds + PG8_SB(b, h) + boff + n * 2048 + k * 1024); } while (0)
; #define PG8_MMA(ai, bj, At, Bt) do { __builtin_amdgcn_s_setprio(1); _Pragma("unroll") for (int m = 0; m < 4; ++m) _Pragma("unroll") for (int n = 0; n < 2; ++n) _Pragma("unroll") for (int k = 0; k < 2; ++k) \
;         acc[ai][bj][m][n] = __builtin_amdgcn_mfma_f32_16x16x32_bf16(Bt[n][k], At[m][k], acc[ai][bj][m][n], 0, 0, 0); __builtin_amdgcn_s_setprio(0); } while (0)
; #define PG8_WAIT_V(n) asm volatile("s_waitcnt vmcnt(" #n ")" ::: "memory")
; #define PG8_BAR __builtin_amdgcn_s_barrier()
; template <class Epi, class Sched, bool ALIGN_EPI = false, bool SP2 = false>
; __device__ __forceinline__ void gemm_phase(PG8_LAS unsigned char* lds, const Gemm g, const Sched& S, const Epi& E) {
;     ...
;         for (int t = 0; t < nt; t += 2) {
;             const bool last = (t == nt - 2);
;             const char* a1 = cA + (size_t)(t + 1) * kstep;
;             const char* a2 = last ? nA : cA + (size_t)(t + 2) * kstep; const char* b2 = last ? nB : cB + (size_t)(t + 2) * kstep;
;             const char* a3 = a2 + kstep; const char* b3 = b2 + kstep;
;             if (last && has_next) S.a_ready(nxt);
;             if constexpr (SP2) {
;             PG8_LDB(B0, 0, 0); PG8_LDB(B1, 0, 1); PG8_SCHED; PG8_LDA(At, 0, 0); PG8_STAGE(PG8_SA(1, 1), a1 + hstepA, voffA);
;             PG8_WAIT_V(8); PG8_WAIT_L(0); PG8_BAR; PG8_MMA(0, 0, At, B0); PG8_MMA(0, 1, At, B1); PG8_BAR; PG8_SCHED;
;             PG8_LDA(At, 0, 1); PG8_STAGE(PG8_SB(0, 0), b2, voffB); PG8_STAGE(PG8_SB(0, 1), b2 + hstepB, voffB); PG8_STAGE(PG8_SA(0, 0), a2, voffA);
;             PG8_WAIT_V(8); PG8_WAIT_L(0); PG8_BAR; PG8_MMA(1, 0, At, B0); PG8_MMA(1, 1, At, B1); PG8_BAR; PG8_SCHED;
.LBB0_563:
	v_add_u32_e32 v142, s21, v150
	ds_read_b128 v[152:155], v142
	ds_read_b128 v[156:159], v142 offset:1024
	ds_read_b128 v[160:163], v142 offset:2048
	ds_read_b128 v[164:167], v142 offset:3072
	v_add_u32_e32 v142, s91, v150
	s_add_u32 s24, s88, s14
	ds_read_b128 v[168:171], v142
	ds_read_b128 v[172:175], v142 offset:1024
	ds_read_b128 v[176:179], v142 offset:2048
	ds_read_b128 v[180:183], v142 offset:3072
	s_addc_u32 s25, s89, s15
	s_add_u32 s24, s24, 0x4900100
	s_addc_u32 s25, s25, 0
	s_add_u32 s67, s55, s14
	s_addc_u32 s69, s59, s15
	s_cmpk_eq_i32 s14, 0x700
	s_cselect_b32 s27, s97, s25
	s_cselect_b32 s26, s96, s24
	s_cselect_b32 s25, s46, s69
	s_cselect_b32 s24, s54, s67
	v_lshl_add_u64 v[142:143], v[138:139], 0, s[14:15]
	s_add_i32 m0, s34, 0xc000
	ds_read_b128 v[184:187], v151
	ds_read_b128 v[188:191], v151 offset:1024
	ds_read_b128 v[192:195], v151 offset:2048
	ds_read_b128 v[196:199], v151 offset:3072
	ds_read_b128 v[200:203], v151 offset:4096
	ds_read_b128 v[208:211], v151 offset:5120
	ds_read_b128 v[212:215], v151 offset:6144
	ds_read_b128 v[216:219], v151 offset:7168
	global_load_lds_dwordx4 v[142:143], off
	v_lshl_add_u64 v[142:143], v[140:141], 0, s[14:15]
	s_add_i32 m0, s34, 0xe000
	s_nop 0
	global_load_lds_dwordx4 v[142:143], off
	s_waitcnt vmcnt(8)
	s_waitcnt lgkmcnt(0)
	s_barrier
	s_setprio 1
	s_waitcnt lgkmcnt(0)
	v_mfma_f32_16x16x32_bf16 v[126:129], v[152:155], v[184:187], v[126:129]
	v_mfma_f32_16x16x32_bf16 v[122:125], v[160:163], v[184:187], v[122:125]
	v_mfma_f32_16x16x32_bf16 v[110:113], v[152:155], v[192:195], v[110:113]
	v_mfma_f32_16x16x32_bf16 v[106:109], v[160:163], v[192:195], v[106:109]
	v_mfma_f32_16x16x32_bf16 v[94:97], v[152:155], v[200:203], v[94:97]
	v_mfma_f32_16x16x32_bf16 v[90:93], v[160:163], v[200:203], v[90:93]
	v_mfma_f32_16x16x32_bf16 v[78:81], v[152:155], v[212:215], v[78:81]
	v_mfma_f32_16x16x32_bf16 v[74:77], v[160:163], v[212:215], v[74:77]
	v_mfma_f32_16x16x32_bf16 v[126:129], v[156:159], v[188:191], v[126:129]
	v_mfma_f32_16x16x32_bf16 v[122:125], v[164:167], v[188:191], v[122:125]
	v_mfma_f32_16x16x32_bf16 v[110:113], v[156:159], v[196:199], v[110:113]
	v_mfma_f32_16x16x32_bf16 v[106:109], v[164:167], v[196:199], v[106:109]
	v_mfma_f32_16x16x32_bf16 v[94:97], v[156:159], v[208:211], v[94:97]
	v_mfma_f32_16x16x32_bf16 v[90:93], v[164:167], v[208:211], v[90:93]
	v_mfma_f32_16x16x32_bf16 v[78:81], v[156:159], v[216:219], v[78:81]
	v_mfma_f32_16x16x32_bf16 v[74:77], v[164:167], v[216:219], v[74:77]
	s_setprio 0
	s_setprio 1
	v_mfma_f32_16x16x32_bf16 v[118:121], v[168:171], v[184:187], v[118:121]
	v_mfma_f32_16x16x32_bf16 v[114:117], v[176:179], v[184:187], v[114:117]
	v_mfma_f32_16x16x32_bf16 v[102:105], v[168:171], v[192:195], v[102:105]
	v_mfma_f32_16x16x32_bf16 v[98:101], v[176:179], v[192:195], v[98:101]
	v_mfma_f32_16x16x32_bf16 v[86:89], v[168:171], v[200:203], v[86:89]
	v_mfma_f32_16x16x32_bf16 v[82:85], v[176:179], v[200:203], v[82:85]
	v_mfma_f32_16x16x32_bf16 v[70:73], v[168:171], v[212:215], v[70:73]
	v_mfma_f32_16x16x32_bf16 v[66:69], v[176:179], v[212:215], v[66:69]
	v_mfma_f32_16x16x32_bf16 v[118:121], v[172:175], v[188:191], v[118:121]
	v_mfma_f32_16x16x32_bf16 v[114:117], v[180:183], v[188:191], v[114:117]
	v_mfma_f32_16x16x32_bf16 v[102:105], v[172:175], v[196:199], v[102:105]
	v_mfma_f32_16x16x32_bf16 v[98:101], v[180:183], v[196:199], v[98:101]
	v_mfma_f32_16x16x32_bf16 v[86:89], v[172:175], v[208:211], v[86:89]
	v_mfma_f32_16x16x32_bf16 v[82:85], v[180:183], v[208:211], v[82:85]
	v_mfma_f32_16x16x32_bf16 v[70:73], v[172:175], v[216:219], v[70:73]
	v_mfma_f32_16x16x32_bf16 v[66:69], v[180:183], v[216:219], v[66:69]
	s_setprio 0
	s_barrier
	s_add_i32 s67, s21, s31
	v_lshl_add_u64 v[142:143], s[24:25], 0, v[134:135]
	s_mov_b32 m0, s67
	ds_read_b128 v[184:187], v151 offset:16384
	ds_read_b128 v[188:191], v151 offset:17408
	ds_read_b128 v[192:195], v151 offset:18432
	ds_read_b128 v[196:199], v151 offset:19456
	ds_read_b128 v[200:203], v151 offset:20480
	ds_read_b128 v[208:211], v151 offset:21504
	ds_read_b128 v[212:215], v151 offset:22528
	ds_read_b128 v[216:219], v151 offset:23552
	global_load_lds_dwordx4 v[142:143], off
	s_add_i32 m0, s67, 0x2000
	s_add_u32 s70, s24, 0x40000
	v_lshl_add_u64 v[204:205], s[24:25], 0, v[130:131]
	s_addc_u32 s71, s25, 0
	s_add_i32 s67, s91, s31
	global_load_lds_dwordx4 v[204:205], off
	v_lshl_add_u64 v[222:223], s[70:71], 0, v[134:135]
	s_mov_b32 m0, s67
	v_lshl_add_u64 v[224:225], s[26:27], 0, v[132:133]
	global_load_lds_dwordx4 v[222:223], off
	v_lshl_add_u64 v[222:223], s[70:71], 0, v[130:131]
	s_add_i32 m0, s67, 0x2000
	s_nop 0
	global_load_lds_dwordx4 v[222:223], off
	v_lshl_add_u64 v[222:223], s[26:27], 0, v[64:65]
	s_mov_b32 m0, s34
	s_nop 0
	global_load_lds_dwordx4 v[222:223], off
	s_mov_b32 m0, s35
	s_nop 0
	global_load_lds_dwordx4 v[224:225], off
	s_waitcnt vmcnt(8)
	s_waitcnt lgkmcnt(0)
	s_barrier
; #define PG8_STAGE(bufoff, gbase, voff) do { _Pragma("unroll") for (int _i = 0; _i < 2; ++_i) \
;         __builtin_amdgcn_global_load_lds((const unsigned*)((const char*)(gbase) + (voff)[_i]), (PG8_LAS unsigned*)(lds + (bufoff) + ldsw + _i * 8192), 16, 0, 0); } while (0)
; #define PG8_LDA(dst, b, h) do { _Pragma("unroll") for (int m = 0; m < 4; ++m) _Pragma("unroll") for (int k = 0; k < 2; ++k) dst[m][k] = *(const PG8_LAS bf16x8*)(lds + PG8_SA(b, h) + aoff + m * 2048 + k * 1024); } while (0)
; #define PG8_LDB(dst, b, h) do { _Pragma("unroll") for (int n = 0; n < 2; ++n) _Pragma("unroll") for (int k = 0; k < 2; ++k) dst[n][k] = *(const PG8_LAS bf16x8*)(lds + PG8_SB(b, h) + boff + n * 2048 + k * 1024); } while (0)
; #define PG8_MMA(ai, bj, At, Bt) do { __builtin_amdgcn_s_setprio(1); _Pragma("unroll") for (int m = 0; m < 4; ++m) _Pragma("unroll") for (int n = 0; n < 2; ++n) _Pragma("unroll") for (int k = 0; k < 2; ++k) \
;         acc[ai][bj][m][n] = __builtin_amdgcn_mfma_f32_16x16x32_bf16(Bt[n][k], At[m][k], acc[ai][bj][m][n], 0, 0, 0); __builtin_amdgcn_s_setprio(0); } while (0)
; #define PG8_WAIT_V(n) asm volatile("s_waitcnt vmcnt(" #n ")" ::: "memory")
; #define PG8_WAIT_L(n) asm volatile("s_waitcnt lgkmcnt(" #n ")" ::: "memory")
; #define PG8_BAR __builtin_amdgcn_s_barrier()
; #define PG8_SCHED __builtin_amdgcn_sched_barrier(0)
; template <class Epi, class Sched, bool ALIGN_EPI = false, bool SP2 = false>
; __device__ __forceinline__ void gemm_phase(PG8_LAS unsigned char* lds, const Gemm g, const Sched& S, const Epi& E) {
;     ...
;             PG8_WAIT_V(8); PG8_WAIT_L(0); PG8_BAR; PG8_MMA(1, 0, At, B0); PG8_MMA(1, 1, At, B1); PG8_BAR; PG8_SCHED;
;             PG8_LDB(B0, 1, 0); PG8_LDB(B1, 1, 1); PG8_SCHED; PG8_LDA(At, 1, 0); PG8_STAGE(PG8_SA(0, 1), a2 + hstepA, voffA);
;             PG8_WAIT_V(8); PG8_WAIT_L(0); PG8_BAR; PG8_MMA(0, 0, At, B0); PG8_MMA(0, 1, At, B1); PG8_BAR; PG8_SCHED;
	s_setprio 1
	s_waitcnt lgkmcnt(0)
	v_mfma_f32_16x16x32_bf16 v[60:63], v[152:155], v[184:187], v[60:63]
	v_mfma_f32_16x16x32_bf16 v[56:59], v[160:163], v[184:187], v[56:59]
	v_mfma_f32_16x16x32_bf16 v[44:47], v[152:155], v[192:195], v[44:47]
	v_mfma_f32_16x16x32_bf16 v[40:43], v[160:163], v[192:195], v[40:43]
	v_mfma_f32_16x16x32_bf16 v[28:31], v[152:155], v[200:203], v[28:31]
	v_mfma_f32_16x16x32_bf16 v[24:27], v[160:163], v[200:203], v[24:27]
	v_mfma_f32_16x16x32_bf16 v[12:15], v[152:155], v[212:215], v[12:15]
	v_mfma_f32_16x16x32_bf16 v[8:11], v[160:163], v[212:215], v[8:11]
	v_mfma_f32_16x16x32_bf16 v[60:63], v[156:159], v[188:191], v[60:63]
	v_mfma_f32_16x16x32_bf16 v[56:59], v[164:167], v[188:191], v[56:59]
	v_mfma_f32_16x16x32_bf16 v[44:47], v[156:159], v[196:199], v[44:47]
	v_mfma_f32_16x16x32_bf16 v[40:43], v[164:167], v[196:199], v[40:43]
	v_mfma_f32_16x16x32_bf16 v[28:31], v[156:159], v[208:211], v[28:31]
	v_mfma_f32_16x16x32_bf16 v[24:27], v[164:167], v[208:211], v[24:27]
	v_mfma_f32_16x16x32_bf16 v[12:15], v[156:159], v[216:219], v[12:15]
	v_mfma_f32_16x16x32_bf16 v[8:11], v[164:167], v[216:219], v[8:11]
	s_setprio 0
	s_setprio 1
	v_mfma_f32_16x16x32_bf16 v[52:55], v[168:171], v[184:187], v[52:55]
	v_mfma_f32_16x16x32_bf16 v[48:51], v[176:179], v[184:187], v[48:51]
	v_mfma_f32_16x16x32_bf16 v[36:39], v[168:171], v[192:195], v[36:39]
	v_mfma_f32_16x16x32_bf16 v[32:35], v[176:179], v[192:195], v[32:35]
	v_mfma_f32_16x16x32_bf16 v[20:23], v[168:171], v[200:203], v[20:23]
	v_mfma_f32_16x16x32_bf16 v[16:19], v[176:179], v[200:203], v[16:19]
	v_mfma_f32_16x16x32_bf16 v[4:7], v[168:171], v[212:215], v[4:7]
	v_mfma_f32_16x16x32_bf16 v[0:3], v[176:179], v[212:215], v[0:3]
	v_mfma_f32_16x16x32_bf16 v[52:55], v[172:175], v[188:191], v[52:55]
	v_mfma_f32_16x16x32_bf16 v[48:51], v[180:183], v[188:191], v[48:51]
	v_mfma_f32_16x16x32_bf16 v[36:39], v[172:175], v[196:199], v[36:39]
	v_mfma_f32_16x16x32_bf16 v[32:35], v[180:183], v[196:199], v[32:35]
	v_mfma_f32_16x16x32_bf16 v[20:23], v[172:175], v[208:211], v[20:23]
	v_mfma_f32_16x16x32_bf16 v[16:19], v[180:183], v[208:211], v[16:19]
	v_mfma_f32_16x16x32_bf16 v[4:7], v[172:175], v[216:219], v[4:7]
	v_mfma_f32_16x16x32_bf16 v[0:3], v[180:183], v[216:219], v[0:3]
	s_setprio 0
	s_barrier
	v_add_u32_e32 v164, s28, v150
	v_add_u32_e32 v180, s29, v150
	ds_read_b128 v[152:155], v164
	ds_read_b128 v[156:159], v164 offset:1024
	ds_read_b128 v[160:163], v164 offset:2048
	ds_read_b128 v[164:167], v164 offset:3072
	ds_read_b128 v[168:171], v180
	ds_read_b128 v[172:175], v180 offset:1024
	ds_read_b128 v[176:179], v180 offset:2048
	ds_read_b128 v[180:183], v180 offset:3072
	s_add_u32 s26, s26, 0x40000
	s_addc_u32 s27, s27, 0
	s_mov_b32 m0, s44
	v_lshl_add_u64 v[230:231], s[26:27], 0, v[64:65]
	ds_read_b128 v[184:187], v151 offset:32768
	ds_read_b128 v[188:191], v151 offset:33792
	ds_read_b128 v[192:195], v151 offset:34816
	ds_read_b128 v[196:199], v151 offset:35840
	ds_read_b128 v[200:203], v151 offset:36864
	ds_read_b128 v[208:211], v151 offset:37888
	ds_read_b128 v[212:215], v151 offset:38912
	ds_read_b128 v[216:219], v151 offset:39936
	global_load_lds_dwordx4 v[230:231], off
	v_lshl_add_u64 v[230:231], s[26:27], 0, v[132:133]
	s_mov_b32 m0, s45
	s_nop 0
	global_load_lds_dwordx4 v[230:231], off
	s_waitcnt vmcnt(8)
	s_waitcnt lgkmcnt(0)
	s_barrier
	s_setprio 1
	s_waitcnt lgkmcnt(0)
	v_mfma_f32_16x16x32_bf16 v[126:129], v[152:155], v[184:187], v[126:129]
	v_mfma_f32_16x16x32_bf16 v[122:125], v[160:163], v[184:187], v[122:125]
	v_mfma_f32_16x16x32_bf16 v[110:113], v[152:155], v[192:195], v[110:113]
	v_mfma_f32_16x16x32_bf16 v[106:109], v[160:163], v[192:195], v[106:109]
	v_mfma_f32_16x16x32_bf16 v[94:97], v[152:155], v[200:203], v[94:97]
	v_mfma_f32_16x16x32_bf16 v[90:93], v[160:163], v[200:203], v[90:93]
	v_mfma_f32_16x16x32_bf16 v[78:81], v[152:155], v[212:215], v[78:81]
	v_mfma_f32_16x16x32_bf16 v[74:77], v[160:163], v[212:215], v[74:77]
	v_mfma_f32_16x16x32_bf16 v[126:129], v[156:159], v[188:191], v[126:129]
	v_mfma_f32_16x16x32_bf16 v[122:125], v[164:167], v[188:191], v[122:125]
	v_mfma_f32_16x16x32_bf16 v[110:113], v[156:159], v[196:199], v[110:113]
	v_mfma_f32_16x16x32_bf16 v[106:109], v[164:167], v[196:199], v[106:109]
	v_mfma_f32_16x16x32_bf16 v[94:97], v[156:159], v[208:211], v[94:97]
	v_mfma_f32_16x16x32_bf16 v[90:93], v[164:167], v[208:211], v[90:93]
	v_mfma_f32_16x16x32_bf16 v[78:81], v[156:159], v[216:219], v[78:81]
	v_mfma_f32_16x16x32_bf16 v[74:77], v[164:167], v[216:219], v[74:77]
	s_setprio 0
	s_setprio 1
	v_mfma_f32_16x16x32_bf16 v[118:121], v[168:171], v[184:187], v[118:121]
	v_mfma_f32_16x16x32_bf16 v[114:117], v[176:179], v[184:187], v[114:117]
	v_mfma_f32_16x16x32_bf16 v[102:105], v[168:171], v[192:195], v[102:105]
	v_mfma_f32_16x16x32_bf16 v[98:101], v[176:179], v[192:195], v[98:101]
	v_mfma_f32_16x16x32_bf16 v[86:89], v[168:171], v[200:203], v[86:89]
	v_mfma_f32_16x16x32_bf16 v[82:85], v[176:179], v[200:203], v[82:85]
	v_mfma_f32_16x16x32_bf16 v[70:73], v[168:171], v[212:215], v[70:73]
	v_mfma_f32_16x16x32_bf16 v[66:69], v[176:179], v[212:215], v[66:69]
	v_mfma_f32_16x16x32_bf16 v[118:121], v[172:175], v[188:191], v[118:121]
	v_mfma_f32_16x16x32_bf16 v[114:117], v[180:183], v[188:191], v[114:117]
	v_mfma_f32_16x16x32_bf16 v[102:105], v[172:175], v[196:199], v[102:105]
	v_mfma_f32_16x16x32_bf16 v[98:101], v[180:183], v[196:199], v[98:101]
	v_mfma_f32_16x16x32_bf16 v[86:89], v[172:175], v[208:211], v[86:89]
	v_mfma_f32_16x16x32_bf16 v[82:85], v[180:183], v[208:211], v[82:85]
	v_mfma_f32_16x16x32_bf16 v[70:73], v[172:175], v[216:219], v[70:73]
	v_mfma_f32_16x16x32_bf16 v[66:69], v[180:183], v[216:219], v[66:69]
	s_setprio 0
	s_barrier
; #define PG8_STAGE(bufoff, gbase, voff) do { _Pragma("unroll") for (int _i = 0; _i < 2; ++_i) \
;         __builtin_amdgcn_global_load_lds((const unsigned*)((const char*)(gbase) + (voff)[_i]), (PG8_LAS unsigned*)(lds + (bufoff) + ldsw + _i * 8192), 16, 0, 0); } while (0)
; #define PG8_LDA(dst, b, h) do { _Pragma("unroll") for (int m = 0; m < 4; ++m) _Pragma("unroll") for (int k = 0; k < 2; ++k) dst[m][k] = *(const PG8_LAS bf16x8*)(lds + PG8_SA(b, h) + aoff + m * 2048 + k * 1024); } while (0)
; #define PG8_MMA(ai, bj, At, Bt) do { __builtin_amdgcn_s_setprio(1); _Pragma("unroll") for (int m = 0; m < 4; ++m) _Pragma("unroll") for (int n = 0; n < 2; ++n) _Pragma("unroll") for (int k = 0; k < 2; ++k) \
;         acc[ai][bj][m][n] = __builtin_amdgcn_mfma_f32_16x16x32_bf16(Bt[n][k], At[m][k], acc[ai][bj][m][n], 0, 0, 0); __builtin_amdgcn_s_setprio(0); } while (0)
; #define PG8_WAIT_V(n) asm volatile("s_waitcnt vmcnt(" #n ")" ::: "memory")
; #define PG8_WAIT_L(n) asm volatile("s_waitcnt lgkmcnt(" #n ")" ::: "memory")
; #define PG8_BAR __builtin_amdgcn_s_barrier()
; #define PG8_SCHED __builtin_amdgcn_sched_barrier(0)
; template <class Epi, class Sched, bool ALIGN_EPI = false, bool SP2 = false>
; __device__ __forceinline__ void gemm_phase(PG8_LAS unsigned char* lds, const Gemm g, const Sched& S, const Epi& E) {
;     ...
;         for (int t = 0; t < nt; t += 2) {
;             const bool last = (t == nt - 2);
;     ...
;             PG8_LDA(At, 1, 1); PG8_STAGE(PG8_SB(1, 0), b3, voffB); PG8_STAGE(PG8_SB(1, 1), b3 + hstepB, voffB); PG8_STAGE(PG8_SA(1, 0), a3, voffA);
;             PG8_WAIT_V(8); PG8_WAIT_L(0); PG8_BAR; PG8_MMA(1, 0, At, B0); PG8_MMA(1, 1, At, B1); PG8_BAR; PG8_SCHED;
	s_add_i32 s26, s28, s31
	v_lshl_add_u64 v[142:143], v[142:143], 0, s[50:51]
	s_mov_b32 m0, s26
	ds_read_b128 v[184:187], v151 offset:49152
	ds_read_b128 v[188:191], v151 offset:50176
	ds_read_b128 v[192:195], v151 offset:51200
	ds_read_b128 v[196:199], v151 offset:52224
	ds_read_b128 v[200:203], v151 offset:53248
	ds_read_b128 v[208:211], v151 offset:54272
	ds_read_b128 v[212:215], v151 offset:55296
	ds_read_b128 v[216:219], v151 offset:56320
	global_load_lds_dwordx4 v[142:143], off
	s_add_i32 m0, s26, 0x2000
	s_add_u32 s24, s24, 0x40080
	v_lshl_add_u64 v[142:143], v[204:205], 0, s[50:51]
	s_addc_u32 s25, s25, 0
	s_add_i32 s26, s29, s31
	global_load_lds_dwordx4 v[142:143], off
	v_lshl_add_u64 v[142:143], s[24:25], 0, v[134:135]
	s_mov_b32 m0, s26
	s_nop 0
	global_load_lds_dwordx4 v[142:143], off
	v_lshl_add_u64 v[142:143], s[24:25], 0, v[130:131]
	s_add_i32 m0, s26, 0x2000
	s_nop 0
	global_load_lds_dwordx4 v[142:143], off
	v_lshl_add_u64 v[142:143], v[222:223], 0, s[50:51]
	s_mov_b32 m0, s38
	s_nop 0
	global_load_lds_dwordx4 v[142:143], off
	v_lshl_add_u64 v[142:143], v[224:225], 0, s[50:51]
	s_mov_b32 m0, s39
	s_nop 0
	global_load_lds_dwordx4 v[142:143], off
	s_waitcnt vmcnt(8)
	s_waitcnt lgkmcnt(0)
	s_barrier
	s_setprio 1
	s_waitcnt lgkmcnt(0)
	v_mfma_f32_16x16x32_bf16 v[60:63], v[152:155], v[184:187], v[60:63]
	v_mfma_f32_16x16x32_bf16 v[56:59], v[160:163], v[184:187], v[56:59]
	v_mfma_f32_16x16x32_bf16 v[44:47], v[152:155], v[192:195], v[44:47]
	v_mfma_f32_16x16x32_bf16 v[40:43], v[160:163], v[192:195], v[40:43]
	v_mfma_f32_16x16x32_bf16 v[28:31], v[152:155], v[200:203], v[28:31]
	v_mfma_f32_16x16x32_bf16 v[24:27], v[160:163], v[200:203], v[24:27]
	v_mfma_f32_16x16x32_bf16 v[12:15], v[152:155], v[212:215], v[12:15]
	v_mfma_f32_16x16x32_bf16 v[8:11], v[160:163], v[212:215], v[8:11]
	v_mfma_f32_16x16x32_bf16 v[60:63], v[156:159], v[188:191], v[60:63]
	v_mfma_f32_16x16x32_bf16 v[56:59], v[164:167], v[188:191], v[56:59]
	v_mfma_f32_16x16x32_bf16 v[44:47], v[156:159], v[196:199], v[44:47]
	v_mfma_f32_16x16x32_bf16 v[40:43], v[164:167], v[196:199], v[40:43]
	v_mfma_f32_16x16x32_bf16 v[28:31], v[156:159], v[208:211], v[28:31]
	v_mfma_f32_16x16x32_bf16 v[24:27], v[164:167], v[208:211], v[24:27]
	v_mfma_f32_16x16x32_bf16 v[12:15], v[156:159], v[216:219], v[12:15]
	v_mfma_f32_16x16x32_bf16 v[8:11], v[164:167], v[216:219], v[8:11]
	s_setprio 0
	s_setprio 1
	v_mfma_f32_16x16x32_bf16 v[52:55], v[168:171], v[184:187], v[52:55]
	v_mfma_f32_16x16x32_bf16 v[48:51], v[176:179], v[184:187], v[48:51]
	v_mfma_f32_16x16x32_bf16 v[36:39], v[168:171], v[192:195], v[36:39]
	v_mfma_f32_16x16x32_bf16 v[32:35], v[176:179], v[192:195], v[32:35]
	v_mfma_f32_16x16x32_bf16 v[20:23], v[168:171], v[200:203], v[20:23]
	v_mfma_f32_16x16x32_bf16 v[16:19], v[176:179], v[200:203], v[16:19]
	v_mfma_f32_16x16x32_bf16 v[4:7], v[168:171], v[212:215], v[4:7]
	v_mfma_f32_16x16x32_bf16 v[0:3], v[176:179], v[212:215], v[0:3]
	v_mfma_f32_16x16x32_bf16 v[52:55], v[172:175], v[188:191], v[52:55]
	v_mfma_f32_16x16x32_bf16 v[48:51], v[180:183], v[188:191], v[48:51]
	v_mfma_f32_16x16x32_bf16 v[36:39], v[172:175], v[196:199], v[36:39]
	v_mfma_f32_16x16x32_bf16 v[32:35], v[180:183], v[196:199], v[32:35]
	v_mfma_f32_16x16x32_bf16 v[20:23], v[172:175], v[208:211], v[20:23]
	v_mfma_f32_16x16x32_bf16 v[16:19], v[180:183], v[208:211], v[16:19]
	v_mfma_f32_16x16x32_bf16 v[4:7], v[172:175], v[216:219], v[4:7]
	v_mfma_f32_16x16x32_bf16 v[0:3], v[180:183], v[216:219], v[0:3]
	s_setprio 0
	s_add_i32 s62, s62, 2
	s_add_u32 s14, s14, 0x100
	s_addc_u32 s15, s15, 0
	s_cmp_gt_u32 s62, 13
	s_barrier
	s_cbranch_scc0 .LBB0_563
	s_and_b64 vcc, exec, s[10:11]
	s_cbranch_vccz .LBB0_566
	s_barrier

; #define PG8_STAGE(bufoff, gbase, voff) do { _Pragma("unroll") for (int _i = 0; _i < 2; ++_i) \
;         __builtin_amdgcn_global_load_lds((const unsigned*)((const char*)(gbase) + (voff)[_i]), (PG8_LAS unsigned*)(lds + (bufoff) + ldsw + _i * 8192), 16, 0, 0); } while (0)
; #define PG8_LDA(dst, b, h) do { _Pragma("unroll") for (int m = 0; m < 4; ++m) _Pragma("unroll") for (int k = 0; k < 2; ++k) dst[m][k] = *(const PG8_LAS bf16x8*)(lds + PG8_SA(b, h) + aoff + m * 2048 + k * 1024); } while (0)
; #define PG8_LDB(dst, b, h) do { _Pragma("unroll") for (int n = 0; n < 2; ++n) _Pragma("unroll") for (int k = 0; k < 2; ++k) dst[n][k] = *(const PG8_LAS bf16x8*)(lds + PG8_SB(b, h) + boff + n * 2048 + k * 1024); } while (0)
; #define PG8_MMA(ai, bj, At, Bt) do { __builtin_amdgcn_s_setprio(1); _Pragma("unroll") for (int m = 0; m < 4; ++m) _Pragma("unroll") for (int n = 0; n < 2; ++n) _Pragma("unroll") for (int k = 0; k < 2; ++k) \
;         acc[ai][bj][m][n] = __builtin_amdgcn_mfma_f32_16x16x32_bf16(Bt[n][k], At[m][k], acc[ai][bj][m][n], 0, 0, 0); __builtin_amdgcn_s_setprio(0); } while (0)
; #define PG8_WAIT_V(n) asm volatile("s_waitcnt vmcnt(" #n ")" ::: "memory")
; #define PG8_BAR __builtin_amdgcn_s_barrier()
; template <class Epi, class Sched, bool ALIGN_EPI = false, bool SP2 = false>
; __device__ __forceinline__ void gemm_phase(PG8_LAS unsigned char* lds, const Gemm g, const Sched& S, const Epi& E) {
;     ...
;         for (int t = 0; t < nt; t += 2) {
;             const bool last = (t == nt - 2);
;             const char* a1 = cA + (size_t)(t + 1) * kstep;
;             const char* a2 = last ? nA : cA + (size_t)(t + 2) * kstep; const char* b2 = last ? nB : cB + (size_t)(t + 2) * kstep;
;             const char* a3 = a2 + kstep; const char* b3 = b2 + kstep;
;             if (last && has_next) S.a_ready(nxt);
;             if constexpr (SP2) {
;             PG8_LDB(B0, 0, 0); PG8_LDB(B1, 0, 1); PG8_SCHED; PG8_LDA(At, 0, 0); PG8_STAGE(PG8_SA(1, 1), a1 + hstepA, voffA);
;             PG8_WAIT_V(8); PG8_WAIT_L(0); PG8_BAR; PG8_MMA(0, 0, At, B0); PG8_MMA(0, 1, At, B1); PG8_BAR; PG8_SCHED;
;             PG8_LDA(At, 0, 1); PG8_STAGE(PG8_SB(0, 0), b2, voffB); PG8_STAGE(PG8_SB(0, 1), b2 + hstepB, voffB); PG8_STAGE(PG8_SA(0, 0), a2, voffA);
;             PG8_WAIT_V(8); PG8_WAIT_L(0); PG8_BAR; PG8_MMA(1, 0, At, B0); PG8_MMA(1, 1, At, B1); PG8_BAR; PG8_SCHED;
.LBB0_577:
	v_add_u32_e32 v162, s21, v142
	v_add_u32_e32 v178, s91, v142
	s_add_u32 s24, s14, 0x100
	ds_read_b128 v[150:153], v162
	ds_read_b128 v[154:157], v162 offset:1024
	ds_read_b128 v[158:161], v162 offset:2048
	ds_read_b128 v[162:165], v162 offset:3072
	ds_read_b128 v[166:169], v178
	ds_read_b128 v[170:173], v178 offset:1024
	ds_read_b128 v[174:177], v178 offset:2048
	ds_read_b128 v[178:181], v178 offset:3072
	s_addc_u32 s25, s15, 0
	s_add_u32 s26, s46, s14
	s_addc_u32 s27, s54, s15
	s_cmp_eq_u32 s55, 40
	s_cselect_b32 s69, 0, s24
	s_cselect_b32 s67, 0, s25
	s_cselect_b32 s38, s12, s26
	s_cselect_b32 s39, s13, s27
	s_add_u32 s26, s92, s69
	s_addc_u32 s27, s93, s67
	v_lshl_add_u64 v[216:217], v[138:139], 0, s[14:15]
	s_add_i32 m0, s34, 0xc000
	ds_read_b128 v[182:185], v143
	ds_read_b128 v[186:189], v143 offset:1024
	ds_read_b128 v[190:193], v143 offset:2048
	ds_read_b128 v[194:197], v143 offset:3072
	ds_read_b128 v[198:201], v143 offset:4096
	ds_read_b128 v[202:205], v143 offset:5120
	ds_read_b128 v[208:211], v143 offset:6144
	ds_read_b128 v[212:215], v143 offset:7168
	global_load_lds_dwordx4 v[216:217], off
	v_lshl_add_u64 v[216:217], v[140:141], 0, s[14:15]
	s_add_i32 m0, s34, 0xe000
	s_nop 0
	global_load_lds_dwordx4 v[216:217], off
	s_waitcnt vmcnt(8)
	s_waitcnt lgkmcnt(0)
	s_barrier
	s_setprio 1
	s_waitcnt lgkmcnt(0)
	v_mfma_f32_16x16x32_bf16 v[126:129], v[150:153], v[182:185], v[126:129]
	v_mfma_f32_16x16x32_bf16 v[122:125], v[158:161], v[182:185], v[122:125]
	v_mfma_f32_16x16x32_bf16 v[118:121], v[150:153], v[190:193], v[118:121]
	v_mfma_f32_16x16x32_bf16 v[114:117], v[158:161], v[190:193], v[114:117]
	v_mfma_f32_16x16x32_bf16 v[102:105], v[150:153], v[198:201], v[102:105]
	v_mfma_f32_16x16x32_bf16 v[98:101], v[158:161], v[198:201], v[98:101]
	v_mfma_f32_16x16x32_bf16 v[86:89], v[150:153], v[208:211], v[86:89]
	v_mfma_f32_16x16x32_bf16 v[82:85], v[158:161], v[208:211], v[82:85]
	v_mfma_f32_16x16x32_bf16 v[126:129], v[154:157], v[186:189], v[126:129]
	v_mfma_f32_16x16x32_bf16 v[122:125], v[162:165], v[186:189], v[122:125]
	v_mfma_f32_16x16x32_bf16 v[118:121], v[154:157], v[194:197], v[118:121]
	v_mfma_f32_16x16x32_bf16 v[114:117], v[162:165], v[194:197], v[114:117]
	v_mfma_f32_16x16x32_bf16 v[102:105], v[154:157], v[202:205], v[102:105]
	v_mfma_f32_16x16x32_bf16 v[98:101], v[162:165], v[202:205], v[98:101]
	v_mfma_f32_16x16x32_bf16 v[86:89], v[154:157], v[212:215], v[86:89]
	v_mfma_f32_16x16x32_bf16 v[82:85], v[162:165], v[212:215], v[82:85]
	s_setprio 0
	s_setprio 1
	v_mfma_f32_16x16x32_bf16 v[110:113], v[166:169], v[182:185], v[110:113]
	v_mfma_f32_16x16x32_bf16 v[106:109], v[174:177], v[182:185], v[106:109]
	v_mfma_f32_16x16x32_bf16 v[94:97], v[166:169], v[190:193], v[94:97]
	v_mfma_f32_16x16x32_bf16 v[90:93], v[174:177], v[190:193], v[90:93]
	v_mfma_f32_16x16x32_bf16 v[78:81], v[166:169], v[198:201], v[78:81]
	v_mfma_f32_16x16x32_bf16 v[74:77], v[174:177], v[198:201], v[74:77]
	v_mfma_f32_16x16x32_bf16 v[70:73], v[166:169], v[208:211], v[70:73]
	v_mfma_f32_16x16x32_bf16 v[66:69], v[174:177], v[208:211], v[66:69]
	v_mfma_f32_16x16x32_bf16 v[110:113], v[170:173], v[186:189], v[110:113]
	v_mfma_f32_16x16x32_bf16 v[106:109], v[178:181], v[186:189], v[106:109]
	v_mfma_f32_16x16x32_bf16 v[94:97], v[170:173], v[194:197], v[94:97]
	v_mfma_f32_16x16x32_bf16 v[90:93], v[178:181], v[194:197], v[90:93]
	v_mfma_f32_16x16x32_bf16 v[78:81], v[170:173], v[202:205], v[78:81]
	v_mfma_f32_16x16x32_bf16 v[74:77], v[178:181], v[202:205], v[74:77]
	v_mfma_f32_16x16x32_bf16 v[70:73], v[170:173], v[212:215], v[70:73]
	v_mfma_f32_16x16x32_bf16 v[66:69], v[178:181], v[212:215], v[66:69]
	s_setprio 0
	s_barrier
	s_add_i32 s14, s21, s31
	v_lshl_add_u64 v[216:217], s[38:39], 0, v[134:135]
	s_mov_b32 m0, s14
	ds_read_b128 v[182:185], v143 offset:16384
	ds_read_b128 v[186:189], v143 offset:17408
	ds_read_b128 v[190:193], v143 offset:18432
	ds_read_b128 v[194:197], v143 offset:19456
	ds_read_b128 v[198:201], v143 offset:20480
	ds_read_b128 v[202:205], v143 offset:21504
	ds_read_b128 v[208:211], v143 offset:22528
	ds_read_b128 v[212:215], v143 offset:23552
	global_load_lds_dwordx4 v[216:217], off
	s_add_i32 m0, s14, 0x2000
	s_add_u32 s14, s38, 0xb0000
	v_lshl_add_u64 v[218:219], s[38:39], 0, v[130:131]
	s_addc_u32 s15, s39, 0
	s_add_i32 s67, s91, s31
	global_load_lds_dwordx4 v[218:219], off
	v_lshl_add_u64 v[222:223], s[14:15], 0, v[134:135]
	s_mov_b32 m0, s67
	v_lshl_add_u64 v[224:225], s[26:27], 0, v[132:133]
	global_load_lds_dwordx4 v[222:223], off
	v_lshl_add_u64 v[222:223], s[14:15], 0, v[130:131]
	s_add_i32 m0, s67, 0x2000
	s_nop 0
	global_load_lds_dwordx4 v[222:223], off
	v_lshl_add_u64 v[222:223], s[26:27], 0, v[64:65]
	s_mov_b32 m0, s34
	s_nop 0
	global_load_lds_dwordx4 v[222:223], off
	s_mov_b32 m0, s35
	s_nop 0
	global_load_lds_dwordx4 v[224:225], off
	s_waitcnt vmcnt(8)
	s_waitcnt lgkmcnt(0)
	s_barrier
; #define PG8_STAGE(bufoff, gbase, voff) do { _Pragma("unroll") for (int _i = 0; _i < 2; ++_i) \
;         __builtin_amdgcn_global_load_lds((const unsigned*)((const char*)(gbase) + (voff)[_i]), (PG8_LAS unsigned*)(lds + (bufoff) + ldsw + _i * 8192), 16, 0, 0); } while (0)
; #define PG8_LDA(dst, b, h) do { _Pragma("unroll") for (int m = 0; m < 4; ++m) _Pragma("unroll") for (int k = 0; k < 2; ++k) dst[m][k] = *(const PG8_LAS bf16x8*)(lds + PG8_SA(b, h) + aoff + m * 2048 + k * 1024); } while (0)
; #define PG8_LDB(dst, b, h) do { _Pragma("unroll") for (int n = 0; n < 2; ++n) _Pragma("unroll") for (int k = 0; k < 2; ++k) dst[n][k] = *(const PG8_LAS bf16x8*)(lds + PG8_SB(b, h) + boff + n * 2048 + k * 1024); } while (0)
; #define PG8_MMA(ai, bj, At, Bt) do { __builtin_amdgcn_s_setprio(1); _Pragma("unroll") for (int m = 0; m < 4; ++m) _Pragma("unroll") for (int n = 0; n < 2; ++n) _Pragma("unroll") for (int k = 0; k < 2; ++k) \
;         acc[ai][bj][m][n] = __builtin_amdgcn_mfma_f32_16x16x32_bf16(Bt[n][k], At[m][k], acc[ai][bj][m][n], 0, 0, 0); __builtin_amdgcn_s_setprio(0); } while (0)
; #define PG8_WAIT_V(n) asm volatile("s_waitcnt vmcnt(" #n ")" ::: "memory")
; #define PG8_WAIT_L(n) asm volatile("s_waitcnt lgkmcnt(" #n ")" ::: "memory")
; #define PG8_BAR __builtin_amdgcn_s_barrier()
; #define PG8_SCHED __builtin_amdgcn_sched_barrier(0)
; template <class Epi, class Sched, bool ALIGN_EPI = false, bool SP2 = false>
; __device__ __forceinline__ void gemm_phase(PG8_LAS unsigned char* lds, const Gemm g, const Sched& S, const Epi& E) {
;     ...
;             PG8_WAIT_V(8); PG8_WAIT_L(0); PG8_BAR; PG8_MMA(1, 0, At, B0); PG8_MMA(1, 1, At, B1); PG8_BAR; PG8_SCHED;
;             PG8_LDB(B0, 1, 0); PG8_LDB(B1, 1, 1); PG8_SCHED; PG8_LDA(At, 1, 0); PG8_STAGE(PG8_SA(0, 1), a2 + hstepA, voffA);
;             PG8_WAIT_V(8); PG8_WAIT_L(0); PG8_BAR; PG8_MMA(0, 0, At, B0); PG8_MMA(0, 1, At, B1); PG8_BAR; PG8_SCHED;
	s_setprio 1
	s_waitcnt lgkmcnt(0)
	v_mfma_f32_16x16x32_bf16 v[60:63], v[150:153], v[182:185], v[60:63]
	v_mfma_f32_16x16x32_bf16 v[56:59], v[158:161], v[182:185], v[56:59]
	v_mfma_f32_16x16x32_bf16 v[52:55], v[150:153], v[190:193], v[52:55]
	v_mfma_f32_16x16x32_bf16 v[48:51], v[158:161], v[190:193], v[48:51]
	v_mfma_f32_16x16x32_bf16 v[36:39], v[150:153], v[198:201], v[36:39]
	v_mfma_f32_16x16x32_bf16 v[32:35], v[158:161], v[198:201], v[32:35]
	v_mfma_f32_16x16x32_bf16 v[20:23], v[150:153], v[208:211], v[20:23]
	v_mfma_f32_16x16x32_bf16 v[16:19], v[158:161], v[208:211], v[16:19]
	v_mfma_f32_16x16x32_bf16 v[60:63], v[154:157], v[186:189], v[60:63]
	v_mfma_f32_16x16x32_bf16 v[56:59], v[162:165], v[186:189], v[56:59]
	v_mfma_f32_16x16x32_bf16 v[52:55], v[154:157], v[194:197], v[52:55]
	v_mfma_f32_16x16x32_bf16 v[48:51], v[162:165], v[194:197], v[48:51]
	v_mfma_f32_16x16x32_bf16 v[36:39], v[154:157], v[202:205], v[36:39]
	v_mfma_f32_16x16x32_bf16 v[32:35], v[162:165], v[202:205], v[32:35]
	v_mfma_f32_16x16x32_bf16 v[20:23], v[154:157], v[212:215], v[20:23]
	v_mfma_f32_16x16x32_bf16 v[16:19], v[162:165], v[212:215], v[16:19]
	s_setprio 0
	s_setprio 1
	v_mfma_f32_16x16x32_bf16 v[44:47], v[166:169], v[182:185], v[44:47]
	v_mfma_f32_16x16x32_bf16 v[40:43], v[174:177], v[182:185], v[40:43]
	v_mfma_f32_16x16x32_bf16 v[28:31], v[166:169], v[190:193], v[28:31]
	v_mfma_f32_16x16x32_bf16 v[24:27], v[174:177], v[190:193], v[24:27]
	v_mfma_f32_16x16x32_bf16 v[12:15], v[166:169], v[198:201], v[12:15]
	v_mfma_f32_16x16x32_bf16 v[8:11], v[174:177], v[198:201], v[8:11]
	v_mfma_f32_16x16x32_bf16 v[4:7], v[166:169], v[208:211], v[4:7]
	v_mfma_f32_16x16x32_bf16 v[0:3], v[174:177], v[208:211], v[0:3]
	v_mfma_f32_16x16x32_bf16 v[44:47], v[170:173], v[186:189], v[44:47]
	v_mfma_f32_16x16x32_bf16 v[40:43], v[178:181], v[186:189], v[40:43]
	v_mfma_f32_16x16x32_bf16 v[28:31], v[170:173], v[194:197], v[28:31]
	v_mfma_f32_16x16x32_bf16 v[24:27], v[178:181], v[194:197], v[24:27]
	v_mfma_f32_16x16x32_bf16 v[12:15], v[170:173], v[202:205], v[12:15]
	v_mfma_f32_16x16x32_bf16 v[8:11], v[178:181], v[202:205], v[8:11]
	v_mfma_f32_16x16x32_bf16 v[4:7], v[170:173], v[212:215], v[4:7]
	v_mfma_f32_16x16x32_bf16 v[0:3], v[178:181], v[212:215], v[0:3]
	s_setprio 0
	s_barrier
	v_add_u32_e32 v162, s28, v142
	v_add_u32_e32 v178, s29, v142
	ds_read_b128 v[150:153], v162
	ds_read_b128 v[154:157], v162 offset:1024
	ds_read_b128 v[158:161], v162 offset:2048
	ds_read_b128 v[162:165], v162 offset:3072
	ds_read_b128 v[166:169], v178
	ds_read_b128 v[170:173], v178 offset:1024
	ds_read_b128 v[174:177], v178 offset:2048
	ds_read_b128 v[178:181], v178 offset:3072
	s_add_u32 s14, s26, 0xb0000
	s_addc_u32 s15, s27, 0
	s_mov_b32 m0, s44
	v_lshl_add_u64 v[230:231], s[14:15], 0, v[64:65]
	ds_read_b128 v[182:185], v143 offset:32768
	ds_read_b128 v[186:189], v143 offset:33792
	ds_read_b128 v[190:193], v143 offset:34816
	ds_read_b128 v[194:197], v143 offset:35840
	ds_read_b128 v[198:201], v143 offset:36864
	ds_read_b128 v[202:205], v143 offset:37888
	ds_read_b128 v[208:211], v143 offset:38912
	ds_read_b128 v[212:215], v143 offset:39936
	global_load_lds_dwordx4 v[230:231], off
	v_lshl_add_u64 v[230:231], s[14:15], 0, v[132:133]
	s_mov_b32 m0, s45
	s_nop 0
	global_load_lds_dwordx4 v[230:231], off
	s_waitcnt vmcnt(8)
	s_waitcnt lgkmcnt(0)
	s_barrier
	s_setprio 1
	s_waitcnt lgkmcnt(0)
	v_mfma_f32_16x16x32_bf16 v[126:129], v[150:153], v[182:185], v[126:129]
	v_mfma_f32_16x16x32_bf16 v[122:125], v[158:161], v[182:185], v[122:125]
	v_mfma_f32_16x16x32_bf16 v[118:121], v[150:153], v[190:193], v[118:121]
	v_mfma_f32_16x16x32_bf16 v[114:117], v[158:161], v[190:193], v[114:117]
	v_mfma_f32_16x16x32_bf16 v[102:105], v[150:153], v[198:201], v[102:105]
	v_mfma_f32_16x16x32_bf16 v[98:101], v[158:161], v[198:201], v[98:101]
	v_mfma_f32_16x16x32_bf16 v[86:89], v[150:153], v[208:211], v[86:89]
	v_mfma_f32_16x16x32_bf16 v[82:85], v[158:161], v[208:211], v[82:85]
	v_mfma_f32_16x16x32_bf16 v[126:129], v[154:157], v[186:189], v[126:129]
	v_mfma_f32_16x16x32_bf16 v[122:125], v[162:165], v[186:189], v[122:125]
	v_mfma_f32_16x16x32_bf16 v[118:121], v[154:157], v[194:197], v[118:121]
	v_mfma_f32_16x16x32_bf16 v[114:117], v[162:165], v[194:197], v[114:117]
	v_mfma_f32_16x16x32_bf16 v[102:105], v[154:157], v[202:205], v[102:105]
	v_mfma_f32_16x16x32_bf16 v[98:101], v[162:165], v[202:205], v[98:101]
	v_mfma_f32_16x16x32_bf16 v[86:89], v[154:157], v[212:215], v[86:89]
	v_mfma_f32_16x16x32_bf16 v[82:85], v[162:165], v[212:215], v[82:85]
	s_setprio 0
	s_setprio 1
	v_mfma_f32_16x16x32_bf16 v[110:113], v[166:169], v[182:185], v[110:113]
	v_mfma_f32_16x16x32_bf16 v[106:109], v[174:177], v[182:185], v[106:109]
	v_mfma_f32_16x16x32_bf16 v[94:97], v[166:169], v[190:193], v[94:97]
	v_mfma_f32_16x16x32_bf16 v[90:93], v[174:177], v[190:193], v[90:93]
	v_mfma_f32_16x16x32_bf16 v[78:81], v[166:169], v[198:201], v[78:81]
	v_mfma_f32_16x16x32_bf16 v[74:77], v[174:177], v[198:201], v[74:77]
	v_mfma_f32_16x16x32_bf16 v[70:73], v[166:169], v[208:211], v[70:73]
	v_mfma_f32_16x16x32_bf16 v[66:69], v[174:177], v[208:211], v[66:69]
	v_mfma_f32_16x16x32_bf16 v[110:113], v[170:173], v[186:189], v[110:113]
	v_mfma_f32_16x16x32_bf16 v[106:109], v[178:181], v[186:189], v[106:109]
	v_mfma_f32_16x16x32_bf16 v[94:97], v[170:173], v[194:197], v[94:97]
	v_mfma_f32_16x16x32_bf16 v[90:93], v[178:181], v[194:197], v[90:93]
	v_mfma_f32_16x16x32_bf16 v[78:81], v[170:173], v[202:205], v[78:81]
	v_mfma_f32_16x16x32_bf16 v[74:77], v[178:181], v[202:205], v[74:77]
	v_mfma_f32_16x16x32_bf16 v[70:73], v[170:173], v[212:215], v[70:73]
	v_mfma_f32_16x16x32_bf16 v[66:69], v[178:181], v[212:215], v[66:69]
	s_setprio 0
	s_barrier
; #define PG8_STAGE(bufoff, gbase, voff) do { _Pragma("unroll") for (int _i = 0; _i < 2; ++_i) \
;         __builtin_amdgcn_global_load_lds((const unsigned*)((const char*)(gbase) + (voff)[_i]), (PG8_LAS unsigned*)(lds + (bufoff) + ldsw + _i * 8192), 16, 0, 0); } while (0)
; #define PG8_LDA(dst, b, h) do { _Pragma("unroll") for (int m = 0; m < 4; ++m) _Pragma("unroll") for (int k = 0; k < 2; ++k) dst[m][k] = *(const PG8_LAS bf16x8*)(lds + PG8_SA(b, h) + aoff + m * 2048 + k * 1024); } while (0)
; #define PG8_MMA(ai, bj, At, Bt) do { __builtin_amdgcn_s_setprio(1); _Pragma("unroll") for (int m = 0; m < 4; ++m) _Pragma("unroll") for (int n = 0; n < 2; ++n) _Pragma("unroll") for (int k = 0; k < 2; ++k) \
;         acc[ai][bj][m][n] = __builtin_amdgcn_mfma_f32_16x16x32_bf16(Bt[n][k], At[m][k], acc[ai][bj][m][n], 0, 0, 0); __builtin_amdgcn_s_setprio(0); } while (0)
; #define PG8_WAIT_V(n) asm volatile("s_waitcnt vmcnt(" #n ")" ::: "memory")
; #define PG8_WAIT_L(n) asm volatile("s_waitcnt lgkmcnt(" #n ")" ::: "memory")
; #define PG8_BAR __builtin_amdgcn_s_barrier()
; #define PG8_SCHED __builtin_amdgcn_sched_barrier(0)
; template <class Epi, class Sched, bool ALIGN_EPI = false, bool SP2 = false>
; __device__ __forceinline__ void gemm_phase(PG8_LAS unsigned char* lds, const Gemm g, const Sched& S, const Epi& E) {
;     ...
;         for (int t = 0; t < nt; t += 2) {
;             const bool last = (t == nt - 2);
;     ...
;             PG8_LDA(At, 1, 1); PG8_STAGE(PG8_SB(1, 0), b3, voffB); PG8_STAGE(PG8_SB(1, 1), b3 + hstepB, voffB); PG8_STAGE(PG8_SA(1, 0), a3, voffA);
;             PG8_WAIT_V(8); PG8_WAIT_L(0); PG8_BAR; PG8_MMA(1, 0, At, B0); PG8_MMA(1, 1, At, B1); PG8_BAR; PG8_SCHED;
	s_add_i32 s14, s28, s31
	v_lshl_add_u64 v[216:217], v[216:217], 0, s[50:51]
	s_mov_b32 m0, s14
	ds_read_b128 v[182:185], v143 offset:49152
	ds_read_b128 v[186:189], v143 offset:50176
	ds_read_b128 v[190:193], v143 offset:51200
	ds_read_b128 v[194:197], v143 offset:52224
	ds_read_b128 v[198:201], v143 offset:53248
	ds_read_b128 v[202:205], v143 offset:54272
	ds_read_b128 v[208:211], v143 offset:55296
	ds_read_b128 v[212:215], v143 offset:56320
	global_load_lds_dwordx4 v[216:217], off
	s_add_i32 m0, s14, 0x2000
	s_add_u32 s14, s38, 0xb0080
	v_lshl_add_u64 v[216:217], v[218:219], 0, s[50:51]
	s_addc_u32 s15, s39, 0
	s_add_i32 s26, s29, s31
	global_load_lds_dwordx4 v[216:217], off
	v_lshl_add_u64 v[216:217], s[14:15], 0, v[134:135]
	s_mov_b32 m0, s26
	s_nop 0
	global_load_lds_dwordx4 v[216:217], off
	v_lshl_add_u64 v[216:217], s[14:15], 0, v[130:131]
	s_add_i32 m0, s26, 0x2000
	s_nop 0
	global_load_lds_dwordx4 v[216:217], off
	v_lshl_add_u64 v[216:217], v[222:223], 0, s[50:51]
	s_mov_b32 m0, s52
	s_nop 0
	global_load_lds_dwordx4 v[216:217], off
	v_lshl_add_u64 v[216:217], v[224:225], 0, s[50:51]
	s_mov_b32 m0, s53
	s_nop 0
	global_load_lds_dwordx4 v[216:217], off
	s_waitcnt vmcnt(8)
	s_waitcnt lgkmcnt(0)
	s_barrier
	s_setprio 1
	s_waitcnt lgkmcnt(0)
	v_mfma_f32_16x16x32_bf16 v[60:63], v[150:153], v[182:185], v[60:63]
	v_mfma_f32_16x16x32_bf16 v[56:59], v[158:161], v[182:185], v[56:59]
	v_mfma_f32_16x16x32_bf16 v[52:55], v[150:153], v[190:193], v[52:55]
	v_mfma_f32_16x16x32_bf16 v[48:51], v[158:161], v[190:193], v[48:51]
	v_mfma_f32_16x16x32_bf16 v[36:39], v[150:153], v[198:201], v[36:39]
	v_mfma_f32_16x16x32_bf16 v[32:35], v[158:161], v[198:201], v[32:35]
	v_mfma_f32_16x16x32_bf16 v[20:23], v[150:153], v[208:211], v[20:23]
	v_mfma_f32_16x16x32_bf16 v[16:19], v[158:161], v[208:211], v[16:19]
	v_mfma_f32_16x16x32_bf16 v[60:63], v[154:157], v[186:189], v[60:63]
	v_mfma_f32_16x16x32_bf16 v[56:59], v[162:165], v[186:189], v[56:59]
	v_mfma_f32_16x16x32_bf16 v[52:55], v[154:157], v[194:197], v[52:55]
	v_mfma_f32_16x16x32_bf16 v[48:51], v[162:165], v[194:197], v[48:51]
	v_mfma_f32_16x16x32_bf16 v[36:39], v[154:157], v[202:205], v[36:39]
	v_mfma_f32_16x16x32_bf16 v[32:35], v[162:165], v[202:205], v[32:35]
	v_mfma_f32_16x16x32_bf16 v[20:23], v[154:157], v[212:215], v[20:23]
	v_mfma_f32_16x16x32_bf16 v[16:19], v[162:165], v[212:215], v[16:19]
	s_setprio 0
	s_setprio 1
	v_mfma_f32_16x16x32_bf16 v[44:47], v[166:169], v[182:185], v[44:47]
	v_mfma_f32_16x16x32_bf16 v[40:43], v[174:177], v[182:185], v[40:43]
	v_mfma_f32_16x16x32_bf16 v[28:31], v[166:169], v[190:193], v[28:31]
	v_mfma_f32_16x16x32_bf16 v[24:27], v[174:177], v[190:193], v[24:27]
	v_mfma_f32_16x16x32_bf16 v[12:15], v[166:169], v[198:201], v[12:15]
	v_mfma_f32_16x16x32_bf16 v[8:11], v[174:177], v[198:201], v[8:11]
	v_mfma_f32_16x16x32_bf16 v[4:7], v[166:169], v[208:211], v[4:7]
	v_mfma_f32_16x16x32_bf16 v[0:3], v[174:177], v[208:211], v[0:3]
	v_mfma_f32_16x16x32_bf16 v[44:47], v[170:173], v[186:189], v[44:47]
	v_mfma_f32_16x16x32_bf16 v[40:43], v[178:181], v[186:189], v[40:43]
	v_mfma_f32_16x16x32_bf16 v[28:31], v[170:173], v[194:197], v[28:31]
	v_mfma_f32_16x16x32_bf16 v[24:27], v[178:181], v[194:197], v[24:27]
	v_mfma_f32_16x16x32_bf16 v[12:15], v[170:173], v[202:205], v[12:15]
	v_mfma_f32_16x16x32_bf16 v[8:11], v[178:181], v[202:205], v[8:11]
	v_mfma_f32_16x16x32_bf16 v[4:7], v[170:173], v[212:215], v[4:7]
	v_mfma_f32_16x16x32_bf16 v[0:3], v[178:181], v[212:215], v[0:3]
	s_setprio 0
	s_add_i32 s55, s55, 2
	s_cmp_gt_u32 s55, 41
	s_mov_b64 s[14:15], s[24:25]
	s_barrier
	s_cbranch_scc0 .LBB0_577
	s_and_b64 vcc, exec, s[10:11]
	s_cbranch_vccz .LBB0_580
	s_barrier
